# GEMM main loops: loader segments trimmed further (shared +0x80 base per phase, m0 wait states provided by moved ds_reads instead of s_nop)
# speedup vs baseline: 1.0150x; 1.0026x over previous
;     __device__ __forceinline__ void prep(int pm, int par, LAS unsigned char* lds) const { if (fold) prep_rowstats(stat, pm, par, lds); }
;     __device__ __forceinline__ void prep(int pm, int par, LAS unsigned char* lds) const { if (!ident) prep_rowstats(stat, pm, par, lds); }
;     __device__ __forceinline__ void prep(int pm, int par, LAS unsigned char* lds) const { prep_rowstats(stat, pm, par, lds); }
; #define G_STAGE(bufoff, gbase) do { _Pragma("unroll") for (int _i = 0; _i < 2; ++_i) \
;         __builtin_amdgcn_global_load_lds((const unsigned*)((const char*)(gbase) + voff[_i]), (LAS unsigned*)(lds + (bufoff) + ldsw + _i * 8192), 16, 0, 0); } while (0)
; #define G_LDA(dst, b, h) do { _Pragma("unroll") for (int m = 0; m < 4; ++m) _Pragma("unroll") for (int k = 0; k < 2; ++k) dst[m][k] = *(const LAS bf16x8*)(lds + G_SA(b, h) + aoff + m * 2048 + k * 1024); } while (0)
; #define G_LDB(dst, b, h) do { _Pragma("unroll") for (int n = 0; n < 2; ++n) _Pragma("unroll") for (int k = 0; k < 2; ++k) dst[n][k] = *(const LAS bf16x8*)(lds + G_SB(b, h) + boff + n * 2048 + k * 1024); } while (0)
; #define G_WAIT_L(n) asm volatile("s_waitcnt lgkmcnt(" #n ")" ::: "memory")
; #define G_BAR __builtin_amdgcn_s_barrier()
; #define G_SCHED __builtin_amdgcn_sched_barrier(0)
; template <class Epi>
; __device__ __forceinline__ void gemm_phase(LAS unsigned char* lds, const bf16_t* Ag, const bf16_t* Btg, const int K, const int nM, const int nN, const Epi& E) {
;     ...
;         for (int t = 0; t < nt; t += 2) {
;             const bool last = (t == nt - 2);
;             const char* a1 = cA + (size_t)(t + 1) * kstep;
;             const char* a2 = last ? nA : cA + (size_t)(t + 2) * kstep; const char* b2 = last ? nB : cB + (size_t)(t + 2) * kstep;
;             const char* a3 = a2 + kstep; const char* b3 = b2 + kstep;
;             if (last && has_next && pmn != pm) E.prep(pmn, par ^ 1, lds);
;             G_LDB(B0, 0, 0); G_SCHED; G_LDA(At, 0, 0); G_STAGE(G_SA(1, 1), a1 + hstep);
;             G_WAIT_L(8); G_BAR; G_WAIT_L(0); G_MMA(0, 0, At, B0); G_BAR; G_SCHED;
;             G_LDB(B1, 0, 1); G_STAGE(G_SB(0, 0), b2);
;             G_BAR; G_WAIT_L(0); G_MMA(0, 1, At, B1); G_BAR;
;             G_LDA(At, 0, 1); G_STAGE(G_SA(0, 0), a2);
;             G_BAR; G_WAIT_L(0); G_MMA(1, 0, At, B0); G_BAR; G_SCHED;
;             G_STAGE(G_SB(0, 1), b2 + hstep);
.LBB0_78:
	s_add_u32 s12, s50, 0xfffc0080
	s_addc_u32 s26, s51, -1
	s_and_b64 s[52:53], s[52:53], exec
	s_cselect_b32 s55, s26, s43
	s_cselect_b32 s54, s12, s42
	s_cselect_b32 s53, s72, s15
	s_cselect_b32 s52, s71, s69
	s_add_i32 s12, 0, 0x10000
	v_add_u32_e32 v136, s12, v175
	ds_read_b128 v[124:127], v136
	ds_read_b128 v[128:131], v136 offset:1024
	ds_read_b128 v[132:135], v136 offset:2048
	ds_read_b128 v[136:139], v136 offset:3072
	s_add_i32 m0, s58, 0xc000
	ds_read_b128 v[140:143], v186
	ds_read_b128 v[148:151], v186 offset:1024
	ds_read_b128 v[152:155], v186 offset:2048
	ds_read_b128 v[156:159], v186 offset:3072
	ds_read_b128 v[188:191], v186 offset:4096
	ds_read_b128 v[192:195], v186 offset:5120
	ds_read_b128 v[222:225], v186 offset:6144
	global_load_lds_dwordx4 v170, s[50:51]
	s_add_i32 m0, s58, 0xe000
	ds_read_b128 v[226:229], v186 offset:7168
	global_load_lds_dwordx4 v168, s[50:51]
	s_waitcnt lgkmcnt(8)
	s_barrier
	s_waitcnt lgkmcnt(0)
	s_setprio 1
	s_waitcnt lgkmcnt(0)
	v_mfma_f32_16x16x32_bf16 v[164:167], v[124:127], v[140:143], v[164:167]
	v_mfma_f32_16x16x32_bf16 v[160:163], v[132:135], v[140:143], v[160:163]
	v_mfma_f32_16x16x32_bf16 v[116:119], v[124:127], v[152:155], v[116:119]
	v_mfma_f32_16x16x32_bf16 v[112:115], v[132:135], v[152:155], v[112:115]
	v_mfma_f32_16x16x32_bf16 v[100:103], v[124:127], v[188:191], v[100:103]
	v_mfma_f32_16x16x32_bf16 v[96:99], v[132:135], v[188:191], v[96:99]
	v_mfma_f32_16x16x32_bf16 v[84:87], v[124:127], v[222:225], v[84:87]
	v_mfma_f32_16x16x32_bf16 v[80:83], v[132:135], v[222:225], v[80:83]
	v_mfma_f32_16x16x32_bf16 v[164:167], v[128:131], v[148:151], v[164:167]
	v_mfma_f32_16x16x32_bf16 v[160:163], v[136:139], v[148:151], v[160:163]
	v_mfma_f32_16x16x32_bf16 v[116:119], v[128:131], v[156:159], v[116:119]
	v_mfma_f32_16x16x32_bf16 v[112:115], v[136:139], v[156:159], v[112:115]
	v_mfma_f32_16x16x32_bf16 v[100:103], v[128:131], v[192:195], v[100:103]
	v_mfma_f32_16x16x32_bf16 v[96:99], v[136:139], v[192:195], v[96:99]
	v_mfma_f32_16x16x32_bf16 v[84:87], v[128:131], v[226:229], v[84:87]
	v_mfma_f32_16x16x32_bf16 v[80:83], v[136:139], v[226:229], v[80:83]
	s_setprio 0
	s_barrier
	s_add_i32 s26, 0, 0x14000
	v_add_u32_e32 v172, s26, v175
	s_add_i32 s12, s12, s57
	ds_read_b128 v[230:233], v172
	ds_read_b128 v[234:237], v172 offset:1024
	s_mov_b32 m0, s12
	ds_read_b128 v[238:241], v172 offset:2048
	global_load_lds_dwordx4 v0, s[52:53]
	s_add_i32 m0, s12, 0x2000
	ds_read_b128 v[242:245], v172 offset:3072
	global_load_lds_dwordx4 v2, s[52:53]
	s_barrier
	s_waitcnt lgkmcnt(0)
	s_setprio 1
	s_waitcnt lgkmcnt(0)
	v_mfma_f32_16x16x32_bf16 v[144:147], v[230:233], v[140:143], v[144:147]
	v_mfma_f32_16x16x32_bf16 v[120:123], v[238:241], v[140:143], v[120:123]
	v_mfma_f32_16x16x32_bf16 v[108:111], v[230:233], v[152:155], v[108:111]
	v_mfma_f32_16x16x32_bf16 v[104:107], v[238:241], v[152:155], v[104:107]
	v_mfma_f32_16x16x32_bf16 v[92:95], v[230:233], v[188:191], v[92:95]
	v_mfma_f32_16x16x32_bf16 v[88:91], v[238:241], v[188:191], v[88:91]
	v_mfma_f32_16x16x32_bf16 v[76:79], v[230:233], v[222:225], v[76:79]
	v_mfma_f32_16x16x32_bf16 v[72:75], v[238:241], v[222:225], v[72:75]
	v_mfma_f32_16x16x32_bf16 v[144:147], v[234:237], v[148:151], v[144:147]
	v_mfma_f32_16x16x32_bf16 v[120:123], v[242:245], v[148:151], v[120:123]
	v_mfma_f32_16x16x32_bf16 v[108:111], v[234:237], v[156:159], v[108:111]
	v_mfma_f32_16x16x32_bf16 v[104:107], v[242:245], v[156:159], v[104:107]
	v_mfma_f32_16x16x32_bf16 v[92:95], v[234:237], v[192:195], v[92:95]
	v_mfma_f32_16x16x32_bf16 v[88:91], v[242:245], v[192:195], v[88:91]
	v_mfma_f32_16x16x32_bf16 v[76:79], v[234:237], v[226:229], v[76:79]
	v_mfma_f32_16x16x32_bf16 v[72:75], v[242:245], v[226:229], v[72:75]
	s_setprio 0
	s_mov_b32 m0, s58
	s_barrier
	ds_read_b128 v[140:143], v186 offset:16384
	ds_read_b128 v[148:151], v186 offset:17408
	ds_read_b128 v[152:155], v186 offset:18432
	ds_read_b128 v[156:159], v186 offset:19456
	ds_read_b128 v[188:191], v186 offset:20480
	ds_read_b128 v[192:195], v186 offset:21504
	ds_read_b128 v[222:225], v186 offset:22528
	global_load_lds_dwordx4 v0, s[54:55]
	s_mov_b32 m0, s59
	ds_read_b128 v[226:229], v186 offset:23552
	global_load_lds_dwordx4 v2, s[54:55]
	s_barrier
	s_waitcnt lgkmcnt(0)
	s_setprio 1
	s_waitcnt lgkmcnt(0)
	v_mfma_f32_16x16x32_bf16 v[60:63], v[124:127], v[140:143], v[60:63]
	v_mfma_f32_16x16x32_bf16 v[56:59], v[132:135], v[140:143], v[56:59]
	v_mfma_f32_16x16x32_bf16 v[44:47], v[124:127], v[152:155], v[44:47]
	v_mfma_f32_16x16x32_bf16 v[40:43], v[132:135], v[152:155], v[40:43]
	v_mfma_f32_16x16x32_bf16 v[28:31], v[124:127], v[188:191], v[28:31]
	v_mfma_f32_16x16x32_bf16 v[24:27], v[132:135], v[188:191], v[24:27]
	v_mfma_f32_16x16x32_bf16 v[12:15], v[124:127], v[222:225], v[12:15]
	v_mfma_f32_16x16x32_bf16 v[8:11], v[132:135], v[222:225], v[8:11]
	v_mfma_f32_16x16x32_bf16 v[60:63], v[128:131], v[148:151], v[60:63]
	v_mfma_f32_16x16x32_bf16 v[56:59], v[136:139], v[148:151], v[56:59]
	v_mfma_f32_16x16x32_bf16 v[44:47], v[128:131], v[156:159], v[44:47]
	v_mfma_f32_16x16x32_bf16 v[40:43], v[136:139], v[156:159], v[40:43]
	v_mfma_f32_16x16x32_bf16 v[28:31], v[128:131], v[192:195], v[28:31]
	v_mfma_f32_16x16x32_bf16 v[24:27], v[136:139], v[192:195], v[24:27]
	v_mfma_f32_16x16x32_bf16 v[12:15], v[128:131], v[226:229], v[12:15]
	v_mfma_f32_16x16x32_bf16 v[8:11], v[136:139], v[226:229], v[8:11]
	s_setprio 0
	s_barrier
	s_add_u32 s74, s52, 0x40000
	s_addc_u32 s75, s53, 0
	s_add_i32 s12, s26, s57
	s_mov_b32 m0, s12
	s_nop 0
	global_load_lds_dwordx4 v0, s[74:75]
	s_add_i32 m0, s12, 0x2000
	s_nop 0
	global_load_lds_dwordx4 v2, s[74:75]
	s_waitcnt vmcnt(6)
	s_barrier
; #define G_STAGE(bufoff, gbase) do { _Pragma("unroll") for (int _i = 0; _i < 2; ++_i) \
;         __builtin_amdgcn_global_load_lds((const unsigned*)((const char*)(gbase) + voff[_i]), (LAS unsigned*)(lds + (bufoff) + ldsw + _i * 8192), 16, 0, 0); } while (0)
; #define G_LDA(dst, b, h) do { _Pragma("unroll") for (int m = 0; m < 4; ++m) _Pragma("unroll") for (int k = 0; k < 2; ++k) dst[m][k] = *(const LAS bf16x8*)(lds + G_SA(b, h) + aoff + m * 2048 + k * 1024); } while (0)
; #define G_LDB(dst, b, h) do { _Pragma("unroll") for (int n = 0; n < 2; ++n) _Pragma("unroll") for (int k = 0; k < 2; ++k) dst[n][k] = *(const LAS bf16x8*)(lds + G_SB(b, h) + boff + n * 2048 + k * 1024); } while (0)
; #define G_MMA(ai, bj, At, Bt) do { __builtin_amdgcn_s_setprio(1); _Pragma("unroll") for (int m = 0; m < 4; ++m) _Pragma("unroll") for (int n = 0; n < 2; ++n) _Pragma("unroll") for (int k = 0; k < 2; ++k) \
;         acc[ai][bj][m][n] = MFMA16(Bt[n][k], At[m][k], acc[ai][bj][m][n]); __builtin_amdgcn_s_setprio(0); } while (0)
; #define G_WAIT_V(n) asm volatile("s_waitcnt vmcnt(" #n ")" ::: "memory")
; #define G_WAIT_L(n) asm volatile("s_waitcnt lgkmcnt(" #n ")" ::: "memory")
; #define G_BAR __builtin_amdgcn_s_barrier()
; #define G_SCHED __builtin_amdgcn_sched_barrier(0)
; template <class Epi>
; __device__ __forceinline__ void gemm_phase(LAS unsigned char* lds, const bf16_t* Ag, const bf16_t* Btg, const int K, const int nM, const int nN, const Epi& E) {
;     ...
;             G_WAIT_V(6); G_BAR; G_MMA(1, 1, At, B1); G_BAR;
;             G_LDB(B0, 1, 0); G_SCHED; G_LDA(At, 1, 0); G_STAGE(G_SA(0, 1), a2 + hstep);
;             G_WAIT_L(8); G_BAR; G_WAIT_L(0); G_MMA(0, 0, At, B0); G_BAR; G_SCHED;
;             G_LDB(B1, 1, 1); G_STAGE(G_SB(1, 0), b3);
	s_setprio 1
	v_mfma_f32_16x16x32_bf16 v[68:71], v[230:233], v[140:143], v[68:71]
	v_mfma_f32_16x16x32_bf16 v[64:67], v[238:241], v[140:143], v[64:67]
	v_mfma_f32_16x16x32_bf16 v[52:55], v[230:233], v[152:155], v[52:55]
	v_mfma_f32_16x16x32_bf16 v[48:51], v[238:241], v[152:155], v[48:51]
	v_mfma_f32_16x16x32_bf16 v[36:39], v[230:233], v[188:191], v[36:39]
	v_mfma_f32_16x16x32_bf16 v[32:35], v[238:241], v[188:191], v[32:35]
	v_mfma_f32_16x16x32_bf16 v[20:23], v[230:233], v[222:225], v[20:23]
	v_mfma_f32_16x16x32_bf16 v[16:19], v[238:241], v[222:225], v[16:19]
	v_mfma_f32_16x16x32_bf16 v[68:71], v[234:237], v[148:151], v[68:71]
	v_mfma_f32_16x16x32_bf16 v[64:67], v[242:245], v[148:151], v[64:67]
	v_mfma_f32_16x16x32_bf16 v[52:55], v[234:237], v[156:159], v[52:55]
	v_mfma_f32_16x16x32_bf16 v[48:51], v[242:245], v[156:159], v[48:51]
	v_mfma_f32_16x16x32_bf16 v[36:39], v[234:237], v[192:195], v[36:39]
	v_mfma_f32_16x16x32_bf16 v[32:35], v[242:245], v[192:195], v[32:35]
	v_mfma_f32_16x16x32_bf16 v[20:23], v[234:237], v[226:229], v[20:23]
	v_mfma_f32_16x16x32_bf16 v[16:19], v[242:245], v[226:229], v[16:19]
	s_setprio 0
	s_add_i32 s12, 0, 0x18000
	v_add_u32_e32 v136, s12, v175
	s_barrier
	ds_read_b128 v[124:127], v136
	ds_read_b128 v[128:131], v136 offset:1024
	ds_read_b128 v[132:135], v136 offset:2048
	ds_read_b128 v[136:139], v136 offset:3072
	s_add_u32 s54, s54, 0x40000
	s_addc_u32 s55, s55, 0
	s_mov_b32 m0, s60
	ds_read_b128 v[140:143], v186 offset:32768
	ds_read_b128 v[148:151], v186 offset:33792
	ds_read_b128 v[152:155], v186 offset:34816
	ds_read_b128 v[156:159], v186 offset:35840
	ds_read_b128 v[188:191], v186 offset:36864
	ds_read_b128 v[192:195], v186 offset:37888
	ds_read_b128 v[222:225], v186 offset:38912
	global_load_lds_dwordx4 v0, s[54:55]
	s_mov_b32 m0, s61
	ds_read_b128 v[226:229], v186 offset:39936
	global_load_lds_dwordx4 v2, s[54:55]
	s_waitcnt lgkmcnt(8)
	s_barrier
	s_waitcnt lgkmcnt(0)
	s_setprio 1
	s_waitcnt lgkmcnt(0)
	v_mfma_f32_16x16x32_bf16 v[164:167], v[124:127], v[140:143], v[164:167]
	v_mfma_f32_16x16x32_bf16 v[160:163], v[132:135], v[140:143], v[160:163]
	v_mfma_f32_16x16x32_bf16 v[116:119], v[124:127], v[152:155], v[116:119]
	v_mfma_f32_16x16x32_bf16 v[112:115], v[132:135], v[152:155], v[112:115]
	v_mfma_f32_16x16x32_bf16 v[100:103], v[124:127], v[188:191], v[100:103]
	v_mfma_f32_16x16x32_bf16 v[96:99], v[132:135], v[188:191], v[96:99]
	v_mfma_f32_16x16x32_bf16 v[84:87], v[124:127], v[222:225], v[84:87]
	v_mfma_f32_16x16x32_bf16 v[80:83], v[132:135], v[222:225], v[80:83]
	v_mfma_f32_16x16x32_bf16 v[164:167], v[128:131], v[148:151], v[164:167]
	v_mfma_f32_16x16x32_bf16 v[160:163], v[136:139], v[148:151], v[160:163]
	v_mfma_f32_16x16x32_bf16 v[116:119], v[128:131], v[156:159], v[116:119]
	v_mfma_f32_16x16x32_bf16 v[112:115], v[136:139], v[156:159], v[112:115]
	v_mfma_f32_16x16x32_bf16 v[100:103], v[128:131], v[192:195], v[100:103]
	v_mfma_f32_16x16x32_bf16 v[96:99], v[136:139], v[192:195], v[96:99]
	v_mfma_f32_16x16x32_bf16 v[84:87], v[128:131], v[226:229], v[84:87]
	v_mfma_f32_16x16x32_bf16 v[80:83], v[136:139], v[226:229], v[80:83]
	s_setprio 0
	s_barrier
	s_add_i32 s26, 0, 0x1c000
	s_add_i32 s12, s12, s57
	v_add_u32_e32 v187, s26, v175
	s_mov_b32 m0, s12
	ds_read_b128 v[230:233], v187
	ds_read_b128 v[234:237], v187 offset:1024
	ds_read_b128 v[238:241], v187 offset:2048
	ds_read_b128 v[242:245], v187 offset:3072
	s_add_u32 s98, s52, 0x80
	s_addc_u32 s99, s53, 0
	global_load_lds_dwordx4 v0, s[98:99]
	s_add_i32 m0, s12, 0x2000
	s_nop 0
	global_load_lds_dwordx4 v2, s[98:99]
	s_barrier
; #define G_STAGE(bufoff, gbase) do { _Pragma("unroll") for (int _i = 0; _i < 2; ++_i) \
;         __builtin_amdgcn_global_load_lds((const unsigned*)((const char*)(gbase) + voff[_i]), (LAS unsigned*)(lds + (bufoff) + ldsw + _i * 8192), 16, 0, 0); } while (0)
; #define G_LDA(dst, b, h) do { _Pragma("unroll") for (int m = 0; m < 4; ++m) _Pragma("unroll") for (int k = 0; k < 2; ++k) dst[m][k] = *(const LAS bf16x8*)(lds + G_SA(b, h) + aoff + m * 2048 + k * 1024); } while (0)
; #define G_MMA(ai, bj, At, Bt) do { __builtin_amdgcn_s_setprio(1); _Pragma("unroll") for (int m = 0; m < 4; ++m) _Pragma("unroll") for (int n = 0; n < 2; ++n) _Pragma("unroll") for (int k = 0; k < 2; ++k) \
;         acc[ai][bj][m][n] = MFMA16(Bt[n][k], At[m][k], acc[ai][bj][m][n]); __builtin_amdgcn_s_setprio(0); } while (0)
; #define G_WAIT_V(n) asm volatile("s_waitcnt vmcnt(" #n ")" ::: "memory")
; #define G_WAIT_L(n) asm volatile("s_waitcnt lgkmcnt(" #n ")" ::: "memory")
; #define G_BAR __builtin_amdgcn_s_barrier()
; #define G_SCHED __builtin_amdgcn_sched_barrier(0)
; template <class Epi>
; __device__ __forceinline__ void gemm_phase(LAS unsigned char* lds, const bf16_t* Ag, const bf16_t* Btg, const int K, const int nM, const int nN, const Epi& E) {
;     ...
;         for (int t = 0; t < nt; t += 2) {
;     ...
;             G_BAR; G_WAIT_L(0); G_MMA(0, 1, At, B1); G_BAR;
;             G_LDA(At, 1, 1); G_STAGE(G_SA(1, 0), a3);
;             G_BAR; G_WAIT_L(0); G_MMA(1, 0, At, B0); G_BAR; G_SCHED;
;             G_STAGE(G_SB(1, 1), b3 + hstep);
;             G_WAIT_V(6); G_BAR; G_MMA(1, 1, At, B1); G_BAR;
	s_waitcnt lgkmcnt(0)
	s_setprio 1
	s_waitcnt lgkmcnt(0)
	v_mfma_f32_16x16x32_bf16 v[144:147], v[230:233], v[140:143], v[144:147]
	v_mfma_f32_16x16x32_bf16 v[120:123], v[238:241], v[140:143], v[120:123]
	v_mfma_f32_16x16x32_bf16 v[108:111], v[230:233], v[152:155], v[108:111]
	v_mfma_f32_16x16x32_bf16 v[104:107], v[238:241], v[152:155], v[104:107]
	v_mfma_f32_16x16x32_bf16 v[92:95], v[230:233], v[188:191], v[92:95]
	v_mfma_f32_16x16x32_bf16 v[88:91], v[238:241], v[188:191], v[88:91]
	v_mfma_f32_16x16x32_bf16 v[76:79], v[230:233], v[222:225], v[76:79]
	v_mfma_f32_16x16x32_bf16 v[72:75], v[238:241], v[222:225], v[72:75]
	v_mfma_f32_16x16x32_bf16 v[144:147], v[234:237], v[148:151], v[144:147]
	v_mfma_f32_16x16x32_bf16 v[120:123], v[242:245], v[148:151], v[120:123]
	v_mfma_f32_16x16x32_bf16 v[108:111], v[234:237], v[156:159], v[108:111]
	v_mfma_f32_16x16x32_bf16 v[104:107], v[242:245], v[156:159], v[104:107]
	v_mfma_f32_16x16x32_bf16 v[92:95], v[234:237], v[192:195], v[92:95]
	v_mfma_f32_16x16x32_bf16 v[88:91], v[242:245], v[192:195], v[88:91]
	v_mfma_f32_16x16x32_bf16 v[76:79], v[234:237], v[226:229], v[76:79]
	v_mfma_f32_16x16x32_bf16 v[72:75], v[242:245], v[226:229], v[72:75]
	s_setprio 0
	s_mov_b32 m0, s62
	s_barrier
	ds_read_b128 v[140:143], v186 offset:49152
	ds_read_b128 v[148:151], v186 offset:50176
	ds_read_b128 v[152:155], v186 offset:51200
	ds_read_b128 v[156:159], v186 offset:52224
	ds_read_b128 v[188:191], v186 offset:53248
	ds_read_b128 v[192:195], v186 offset:54272
	ds_read_b128 v[222:225], v186 offset:55296
	ds_read_b128 v[226:229], v186 offset:56320
	s_add_u32 s98, s54, 0xfffc0080
	s_addc_u32 s99, s55, -1
	global_load_lds_dwordx4 v0, s[98:99]
	s_mov_b32 m0, s63
	s_nop 0
	global_load_lds_dwordx4 v2, s[98:99]
	s_barrier
	s_waitcnt lgkmcnt(0)
	s_setprio 1
	s_waitcnt lgkmcnt(0)
	v_mfma_f32_16x16x32_bf16 v[60:63], v[124:127], v[140:143], v[60:63]
	v_mfma_f32_16x16x32_bf16 v[56:59], v[132:135], v[140:143], v[56:59]
	v_mfma_f32_16x16x32_bf16 v[44:47], v[124:127], v[152:155], v[44:47]
	v_mfma_f32_16x16x32_bf16 v[40:43], v[132:135], v[152:155], v[40:43]
	v_mfma_f32_16x16x32_bf16 v[28:31], v[124:127], v[188:191], v[28:31]
	v_mfma_f32_16x16x32_bf16 v[24:27], v[132:135], v[188:191], v[24:27]
	v_mfma_f32_16x16x32_bf16 v[12:15], v[124:127], v[222:225], v[12:15]
	v_mfma_f32_16x16x32_bf16 v[8:11], v[132:135], v[222:225], v[8:11]
	v_mfma_f32_16x16x32_bf16 v[60:63], v[128:131], v[148:151], v[60:63]
	v_mfma_f32_16x16x32_bf16 v[56:59], v[136:139], v[148:151], v[56:59]
	v_mfma_f32_16x16x32_bf16 v[44:47], v[128:131], v[156:159], v[44:47]
	v_mfma_f32_16x16x32_bf16 v[40:43], v[136:139], v[156:159], v[40:43]
	v_mfma_f32_16x16x32_bf16 v[28:31], v[128:131], v[192:195], v[28:31]
	v_mfma_f32_16x16x32_bf16 v[24:27], v[136:139], v[192:195], v[24:27]
	v_mfma_f32_16x16x32_bf16 v[12:15], v[128:131], v[226:229], v[12:15]
	v_mfma_f32_16x16x32_bf16 v[8:11], v[136:139], v[226:229], v[8:11]
	s_setprio 0
	s_barrier
	s_add_u32 s52, s52, 0x40080
	s_addc_u32 s53, s53, 0
	s_add_i32 s12, s26, s57
	s_mov_b32 m0, s12
	s_nop 0
	global_load_lds_dwordx4 v0, s[52:53]
	s_add_i32 m0, s12, 0x2000
	s_nop 0
	global_load_lds_dwordx4 v2, s[52:53]
	s_waitcnt vmcnt(6)
	s_barrier
	s_setprio 1
	v_mfma_f32_16x16x32_bf16 v[68:71], v[230:233], v[140:143], v[68:71]
	v_mfma_f32_16x16x32_bf16 v[64:67], v[238:241], v[140:143], v[64:67]
	v_mfma_f32_16x16x32_bf16 v[52:55], v[230:233], v[152:155], v[52:55]
	v_mfma_f32_16x16x32_bf16 v[48:51], v[238:241], v[152:155], v[48:51]
	v_mfma_f32_16x16x32_bf16 v[36:39], v[230:233], v[188:191], v[36:39]
	v_mfma_f32_16x16x32_bf16 v[32:35], v[238:241], v[188:191], v[32:35]
	v_mfma_f32_16x16x32_bf16 v[20:23], v[230:233], v[222:225], v[20:23]
	v_mfma_f32_16x16x32_bf16 v[16:19], v[238:241], v[222:225], v[16:19]
	v_mfma_f32_16x16x32_bf16 v[68:71], v[234:237], v[148:151], v[68:71]
	v_mfma_f32_16x16x32_bf16 v[64:67], v[242:245], v[148:151], v[64:67]
	v_mfma_f32_16x16x32_bf16 v[52:55], v[234:237], v[156:159], v[52:55]
	v_mfma_f32_16x16x32_bf16 v[48:51], v[242:245], v[156:159], v[48:51]
	v_mfma_f32_16x16x32_bf16 v[36:39], v[234:237], v[192:195], v[36:39]
	v_mfma_f32_16x16x32_bf16 v[32:35], v[242:245], v[192:195], v[32:35]
	v_mfma_f32_16x16x32_bf16 v[20:23], v[234:237], v[226:229], v[20:23]
	v_mfma_f32_16x16x32_bf16 v[16:19], v[242:245], v[226:229], v[16:19]
	s_setprio 0
	s_add_i32 s73, s73, 2
	s_add_u32 s71, s71, 0x100
	s_addc_u32 s72, s72, 0
	s_add_u32 s50, s50, 0x100
	s_addc_u32 s51, s51, 0
	s_cmp_gt_u32 s73, 13
	s_barrier
	s_cbranch_scc1 .LBB0_82

;     __device__ __forceinline__ void prep(int pm, int par, LAS unsigned char* lds) const { if (fold) prep_rowstats(stat, pm, par, lds); }
;     __device__ __forceinline__ void prep(int pm, int par, LAS unsigned char* lds) const { if (!ident) prep_rowstats(stat, pm, par, lds); }
;     __device__ __forceinline__ void prep(int pm, int par, LAS unsigned char* lds) const { prep_rowstats(stat, pm, par, lds); }
; #define G_STAGE(bufoff, gbase) do { _Pragma("unroll") for (int _i = 0; _i < 2; ++_i) \
;         __builtin_amdgcn_global_load_lds((const unsigned*)((const char*)(gbase) + voff[_i]), (LAS unsigned*)(lds + (bufoff) + ldsw + _i * 8192), 16, 0, 0); } while (0)
; #define G_LDA(dst, b, h) do { _Pragma("unroll") for (int m = 0; m < 4; ++m) _Pragma("unroll") for (int k = 0; k < 2; ++k) dst[m][k] = *(const LAS bf16x8*)(lds + G_SA(b, h) + aoff + m * 2048 + k * 1024); } while (0)
; #define G_LDB(dst, b, h) do { _Pragma("unroll") for (int n = 0; n < 2; ++n) _Pragma("unroll") for (int k = 0; k < 2; ++k) dst[n][k] = *(const LAS bf16x8*)(lds + G_SB(b, h) + boff + n * 2048 + k * 1024); } while (0)
; #define G_WAIT_L(n) asm volatile("s_waitcnt lgkmcnt(" #n ")" ::: "memory")
; #define G_BAR __builtin_amdgcn_s_barrier()
; #define G_SCHED __builtin_amdgcn_sched_barrier(0)
; template <class Epi>
; __device__ __forceinline__ void gemm_phase(LAS unsigned char* lds, const bf16_t* Ag, const bf16_t* Btg, const int K, const int nM, const int nN, const Epi& E) {
;     ...
;         for (int t = 0; t < nt; t += 2) {
;             const bool last = (t == nt - 2);
;             const char* a1 = cA + (size_t)(t + 1) * kstep;
;             const char* a2 = last ? nA : cA + (size_t)(t + 2) * kstep; const char* b2 = last ? nB : cB + (size_t)(t + 2) * kstep;
;             const char* a3 = a2 + kstep; const char* b3 = b2 + kstep;
;             if (last && has_next && pmn != pm) E.prep(pmn, par ^ 1, lds);
;             G_LDB(B0, 0, 0); G_SCHED; G_LDA(At, 0, 0); G_STAGE(G_SA(1, 1), a1 + hstep);
;             G_WAIT_L(8); G_BAR; G_WAIT_L(0); G_MMA(0, 0, At, B0); G_BAR; G_SCHED;
;             G_LDB(B1, 0, 1); G_STAGE(G_SB(0, 0), b2);
;             G_BAR; G_WAIT_L(0); G_MMA(0, 1, At, B1); G_BAR;
;             G_LDA(At, 0, 1); G_STAGE(G_SA(0, 0), a2);
;             G_BAR; G_WAIT_L(0); G_MMA(1, 0, At, B0); G_BAR; G_SCHED;
;             G_STAGE(G_SB(0, 1), b2 + hstep);
.LBB0_153:
	s_add_u32 s66, s64, 0x100
	s_addc_u32 s67, s65, 0
	s_and_b64 s[68:69], s[68:69], exec
	s_cselect_b32 s71, s67, s55
	s_cselect_b32 s70, s66, s54
	s_cselect_b32 s69, s61, s14
	s_cselect_b32 s68, s57, s15
	s_add_i32 s12, 0, 0x10000
	v_add_u32_e32 v141, s12, v179
	ds_read_b128 v[144:147], v141
	ds_read_b128 v[148:151], v141 offset:1024
	ds_read_b128 v[152:155], v141 offset:2048
	ds_read_b128 v[156:159], v141 offset:3072
	s_add_i32 m0, s72, 0xc000
	ds_read_b128 v[160:163], v230
	ds_read_b128 v[164:167], v230 offset:1024
	ds_read_b128 v[168:171], v230 offset:2048
	ds_read_b128 v[172:175], v230 offset:3072
	ds_read_b128 v[180:183], v230 offset:4096
	ds_read_b128 v[184:187], v230 offset:5120
	ds_read_b128 v[188:191], v230 offset:6144
	global_load_lds_dwordx4 v138, s[64:65]
	s_add_i32 m0, s72, 0xe000
	ds_read_b128 v[192:195], v230 offset:7168
	global_load_lds_dwordx4 v136, s[64:65]
	s_waitcnt lgkmcnt(8)
	s_barrier
	s_waitcnt lgkmcnt(0)
	s_setprio 1
	s_waitcnt lgkmcnt(0)
	v_mfma_f32_16x16x32_bf16 v[132:135], v[144:147], v[160:163], v[132:135]
	v_mfma_f32_16x16x32_bf16 v[128:131], v[152:155], v[160:163], v[128:131]
	v_mfma_f32_16x16x32_bf16 v[116:119], v[144:147], v[168:171], v[116:119]
	v_mfma_f32_16x16x32_bf16 v[112:115], v[152:155], v[168:171], v[112:115]
	v_mfma_f32_16x16x32_bf16 v[100:103], v[144:147], v[180:183], v[100:103]
	v_mfma_f32_16x16x32_bf16 v[96:99], v[152:155], v[180:183], v[96:99]
	v_mfma_f32_16x16x32_bf16 v[84:87], v[144:147], v[188:191], v[84:87]
	v_mfma_f32_16x16x32_bf16 v[80:83], v[152:155], v[188:191], v[80:83]
	v_mfma_f32_16x16x32_bf16 v[132:135], v[148:151], v[164:167], v[132:135]
	v_mfma_f32_16x16x32_bf16 v[128:131], v[156:159], v[164:167], v[128:131]
	v_mfma_f32_16x16x32_bf16 v[116:119], v[148:151], v[172:175], v[116:119]
	v_mfma_f32_16x16x32_bf16 v[112:115], v[156:159], v[172:175], v[112:115]
	v_mfma_f32_16x16x32_bf16 v[100:103], v[148:151], v[184:187], v[100:103]
	v_mfma_f32_16x16x32_bf16 v[96:99], v[156:159], v[184:187], v[96:99]
	v_mfma_f32_16x16x32_bf16 v[84:87], v[148:151], v[192:195], v[84:87]
	v_mfma_f32_16x16x32_bf16 v[80:83], v[156:159], v[192:195], v[80:83]
	s_setprio 0
	s_barrier
	s_add_i32 s26, 0, 0x14000
	s_add_i32 s12, s12, s21
	v_add_u32_e32 v141, s26, v179
	s_mov_b32 m0, s12
	ds_read_b128 v[232:235], v141
	ds_read_b128 v[236:239], v141 offset:1024
	ds_read_b128 v[240:243], v141 offset:2048
	global_load_lds_dwordx4 v0, s[68:69]
	s_add_i32 m0, s12, 0x2000
	ds_read_b128 v[244:247], v141 offset:3072
	global_load_lds_dwordx4 v2, s[68:69]
	s_barrier
	s_waitcnt lgkmcnt(0)
	s_setprio 1
	s_waitcnt lgkmcnt(0)
	v_mfma_f32_16x16x32_bf16 v[124:127], v[232:235], v[160:163], v[124:127]
	v_mfma_f32_16x16x32_bf16 v[120:123], v[240:243], v[160:163], v[120:123]
	v_mfma_f32_16x16x32_bf16 v[108:111], v[232:235], v[168:171], v[108:111]
	v_mfma_f32_16x16x32_bf16 v[104:107], v[240:243], v[168:171], v[104:107]
	v_mfma_f32_16x16x32_bf16 v[92:95], v[232:235], v[180:183], v[92:95]
	v_mfma_f32_16x16x32_bf16 v[88:91], v[240:243], v[180:183], v[88:91]
	v_mfma_f32_16x16x32_bf16 v[76:79], v[232:235], v[188:191], v[76:79]
	v_mfma_f32_16x16x32_bf16 v[72:75], v[240:243], v[188:191], v[72:75]
	v_mfma_f32_16x16x32_bf16 v[124:127], v[236:239], v[164:167], v[124:127]
	v_mfma_f32_16x16x32_bf16 v[120:123], v[244:247], v[164:167], v[120:123]
	v_mfma_f32_16x16x32_bf16 v[108:111], v[236:239], v[172:175], v[108:111]
	v_mfma_f32_16x16x32_bf16 v[104:107], v[244:247], v[172:175], v[104:107]
	v_mfma_f32_16x16x32_bf16 v[92:95], v[236:239], v[184:187], v[92:95]
	v_mfma_f32_16x16x32_bf16 v[88:91], v[244:247], v[184:187], v[88:91]
	v_mfma_f32_16x16x32_bf16 v[76:79], v[236:239], v[192:195], v[76:79]
	v_mfma_f32_16x16x32_bf16 v[72:75], v[244:247], v[192:195], v[72:75]
	s_setprio 0
	s_mov_b32 m0, s72
	s_barrier
	ds_read_b128 v[160:163], v230 offset:16384
	ds_read_b128 v[164:167], v230 offset:17408
	ds_read_b128 v[168:171], v230 offset:18432
	ds_read_b128 v[172:175], v230 offset:19456
	ds_read_b128 v[180:183], v230 offset:20480
	ds_read_b128 v[184:187], v230 offset:21504
	ds_read_b128 v[188:191], v230 offset:22528
	global_load_lds_dwordx4 v0, s[70:71]
	s_mov_b32 m0, s73
	ds_read_b128 v[192:195], v230 offset:23552
	global_load_lds_dwordx4 v2, s[70:71]
	s_barrier
	s_waitcnt lgkmcnt(0)
	s_setprio 1
	s_waitcnt lgkmcnt(0)
	v_mfma_f32_16x16x32_bf16 v[68:71], v[144:147], v[160:163], v[68:71]
	v_mfma_f32_16x16x32_bf16 v[64:67], v[152:155], v[160:163], v[64:67]
	v_mfma_f32_16x16x32_bf16 v[52:55], v[144:147], v[168:171], v[52:55]
	v_mfma_f32_16x16x32_bf16 v[48:51], v[152:155], v[168:171], v[48:51]
	v_mfma_f32_16x16x32_bf16 v[36:39], v[144:147], v[180:183], v[36:39]
	v_mfma_f32_16x16x32_bf16 v[32:35], v[152:155], v[180:183], v[32:35]
	v_mfma_f32_16x16x32_bf16 v[20:23], v[144:147], v[188:191], v[20:23]
	v_mfma_f32_16x16x32_bf16 v[16:19], v[152:155], v[188:191], v[16:19]
	v_mfma_f32_16x16x32_bf16 v[68:71], v[148:151], v[164:167], v[68:71]
	v_mfma_f32_16x16x32_bf16 v[64:67], v[156:159], v[164:167], v[64:67]
	v_mfma_f32_16x16x32_bf16 v[52:55], v[148:151], v[172:175], v[52:55]
	v_mfma_f32_16x16x32_bf16 v[48:51], v[156:159], v[172:175], v[48:51]
	v_mfma_f32_16x16x32_bf16 v[36:39], v[148:151], v[184:187], v[36:39]
	v_mfma_f32_16x16x32_bf16 v[32:35], v[156:159], v[184:187], v[32:35]
	v_mfma_f32_16x16x32_bf16 v[20:23], v[148:151], v[192:195], v[20:23]
	v_mfma_f32_16x16x32_bf16 v[16:19], v[156:159], v[192:195], v[16:19]
	s_setprio 0
	s_barrier
	s_add_u32 s64, s68, 0x40000
	s_addc_u32 s65, s69, 0
	s_add_i32 s12, s26, s21
	s_mov_b32 m0, s12
	s_nop 0
	global_load_lds_dwordx4 v0, s[64:65]
	s_add_i32 m0, s12, 0x2000
	s_nop 0
	global_load_lds_dwordx4 v2, s[64:65]
	s_waitcnt vmcnt(6)
	s_barrier
; #define G_STAGE(bufoff, gbase) do { _Pragma("unroll") for (int _i = 0; _i < 2; ++_i) \
;         __builtin_amdgcn_global_load_lds((const unsigned*)((const char*)(gbase) + voff[_i]), (LAS unsigned*)(lds + (bufoff) + ldsw + _i * 8192), 16, 0, 0); } while (0)
; #define G_LDA(dst, b, h) do { _Pragma("unroll") for (int m = 0; m < 4; ++m) _Pragma("unroll") for (int k = 0; k < 2; ++k) dst[m][k] = *(const LAS bf16x8*)(lds + G_SA(b, h) + aoff + m * 2048 + k * 1024); } while (0)
; #define G_LDB(dst, b, h) do { _Pragma("unroll") for (int n = 0; n < 2; ++n) _Pragma("unroll") for (int k = 0; k < 2; ++k) dst[n][k] = *(const LAS bf16x8*)(lds + G_SB(b, h) + boff + n * 2048 + k * 1024); } while (0)
; #define G_MMA(ai, bj, At, Bt) do { __builtin_amdgcn_s_setprio(1); _Pragma("unroll") for (int m = 0; m < 4; ++m) _Pragma("unroll") for (int n = 0; n < 2; ++n) _Pragma("unroll") for (int k = 0; k < 2; ++k) \
;         acc[ai][bj][m][n] = MFMA16(Bt[n][k], At[m][k], acc[ai][bj][m][n]); __builtin_amdgcn_s_setprio(0); } while (0)
; #define G_WAIT_V(n) asm volatile("s_waitcnt vmcnt(" #n ")" ::: "memory")
; #define G_WAIT_L(n) asm volatile("s_waitcnt lgkmcnt(" #n ")" ::: "memory")
; #define G_BAR __builtin_amdgcn_s_barrier()
; #define G_SCHED __builtin_amdgcn_sched_barrier(0)
; template <class Epi>
; __device__ __forceinline__ void gemm_phase(LAS unsigned char* lds, const bf16_t* Ag, const bf16_t* Btg, const int K, const int nM, const int nN, const Epi& E) {
;     ...
;             G_WAIT_V(6); G_BAR; G_MMA(1, 1, At, B1); G_BAR;
;             G_LDB(B0, 1, 0); G_SCHED; G_LDA(At, 1, 0); G_STAGE(G_SA(0, 1), a2 + hstep);
;             G_WAIT_L(8); G_BAR; G_WAIT_L(0); G_MMA(0, 0, At, B0); G_BAR; G_SCHED;
;             G_LDB(B1, 1, 1); G_STAGE(G_SB(1, 0), b3);
	s_setprio 1
	v_mfma_f32_16x16x32_bf16 v[60:63], v[232:235], v[160:163], v[60:63]
	v_mfma_f32_16x16x32_bf16 v[56:59], v[240:243], v[160:163], v[56:59]
	v_mfma_f32_16x16x32_bf16 v[44:47], v[232:235], v[168:171], v[44:47]
	v_mfma_f32_16x16x32_bf16 v[40:43], v[240:243], v[168:171], v[40:43]
	v_mfma_f32_16x16x32_bf16 v[28:31], v[232:235], v[180:183], v[28:31]
	v_mfma_f32_16x16x32_bf16 v[24:27], v[240:243], v[180:183], v[24:27]
	v_mfma_f32_16x16x32_bf16 v[12:15], v[232:235], v[188:191], v[12:15]
	v_mfma_f32_16x16x32_bf16 v[8:11], v[240:243], v[188:191], v[8:11]
	v_mfma_f32_16x16x32_bf16 v[60:63], v[236:239], v[164:167], v[60:63]
	v_mfma_f32_16x16x32_bf16 v[56:59], v[244:247], v[164:167], v[56:59]
	v_mfma_f32_16x16x32_bf16 v[44:47], v[236:239], v[172:175], v[44:47]
	v_mfma_f32_16x16x32_bf16 v[40:43], v[244:247], v[172:175], v[40:43]
	v_mfma_f32_16x16x32_bf16 v[28:31], v[236:239], v[184:187], v[28:31]
	v_mfma_f32_16x16x32_bf16 v[24:27], v[244:247], v[184:187], v[24:27]
	v_mfma_f32_16x16x32_bf16 v[12:15], v[236:239], v[192:195], v[12:15]
	v_mfma_f32_16x16x32_bf16 v[8:11], v[244:247], v[192:195], v[8:11]
	s_setprio 0
	s_add_i32 s12, 0, 0x18000
	v_add_u32_e32 v141, s12, v179
	s_barrier
	ds_read_b128 v[144:147], v141
	ds_read_b128 v[148:151], v141 offset:1024
	ds_read_b128 v[152:155], v141 offset:2048
	ds_read_b128 v[156:159], v141 offset:3072
	s_add_u32 s64, s70, 0x40000
	s_addc_u32 s65, s71, 0
	s_mov_b32 m0, s74
	ds_read_b128 v[160:163], v230 offset:32768
	ds_read_b128 v[164:167], v230 offset:33792
	ds_read_b128 v[168:171], v230 offset:34816
	ds_read_b128 v[172:175], v230 offset:35840
	ds_read_b128 v[180:183], v230 offset:36864
	ds_read_b128 v[184:187], v230 offset:37888
	ds_read_b128 v[188:191], v230 offset:38912
	global_load_lds_dwordx4 v0, s[64:65]
	s_mov_b32 m0, s75
	ds_read_b128 v[192:195], v230 offset:39936
	global_load_lds_dwordx4 v2, s[64:65]
	s_waitcnt lgkmcnt(8)
	s_barrier
	s_waitcnt lgkmcnt(0)
	s_setprio 1
	s_waitcnt lgkmcnt(0)
	v_mfma_f32_16x16x32_bf16 v[132:135], v[144:147], v[160:163], v[132:135]
	v_mfma_f32_16x16x32_bf16 v[128:131], v[152:155], v[160:163], v[128:131]
	v_mfma_f32_16x16x32_bf16 v[116:119], v[144:147], v[168:171], v[116:119]
	v_mfma_f32_16x16x32_bf16 v[112:115], v[152:155], v[168:171], v[112:115]
	v_mfma_f32_16x16x32_bf16 v[100:103], v[144:147], v[180:183], v[100:103]
	v_mfma_f32_16x16x32_bf16 v[96:99], v[152:155], v[180:183], v[96:99]
	v_mfma_f32_16x16x32_bf16 v[84:87], v[144:147], v[188:191], v[84:87]
	v_mfma_f32_16x16x32_bf16 v[80:83], v[152:155], v[188:191], v[80:83]
	v_mfma_f32_16x16x32_bf16 v[132:135], v[148:151], v[164:167], v[132:135]
	v_mfma_f32_16x16x32_bf16 v[128:131], v[156:159], v[164:167], v[128:131]
	v_mfma_f32_16x16x32_bf16 v[116:119], v[148:151], v[172:175], v[116:119]
	v_mfma_f32_16x16x32_bf16 v[112:115], v[156:159], v[172:175], v[112:115]
	v_mfma_f32_16x16x32_bf16 v[100:103], v[148:151], v[184:187], v[100:103]
	v_mfma_f32_16x16x32_bf16 v[96:99], v[156:159], v[184:187], v[96:99]
	v_mfma_f32_16x16x32_bf16 v[84:87], v[148:151], v[192:195], v[84:87]
	v_mfma_f32_16x16x32_bf16 v[80:83], v[156:159], v[192:195], v[80:83]
	s_setprio 0
	s_barrier
	s_add_i32 s26, 0, 0x1c000
	s_add_i32 s12, s12, s21
	v_add_u32_e32 v141, s26, v179
	s_mov_b32 m0, s12
	ds_read_b128 v[232:235], v141
	ds_read_b128 v[236:239], v141 offset:1024
	ds_read_b128 v[240:243], v141 offset:2048
	ds_read_b128 v[244:247], v141 offset:3072
	s_add_u32 s98, s68, 0x80
	s_addc_u32 s99, s69, 0
	global_load_lds_dwordx4 v0, s[98:99]
	s_add_i32 m0, s12, 0x2000
	s_nop 0
	global_load_lds_dwordx4 v2, s[98:99]
	s_barrier
; #define G_STAGE(bufoff, gbase) do { _Pragma("unroll") for (int _i = 0; _i < 2; ++_i) \
;         __builtin_amdgcn_global_load_lds((const unsigned*)((const char*)(gbase) + voff[_i]), (LAS unsigned*)(lds + (bufoff) + ldsw + _i * 8192), 16, 0, 0); } while (0)
; #define G_LDA(dst, b, h) do { _Pragma("unroll") for (int m = 0; m < 4; ++m) _Pragma("unroll") for (int k = 0; k < 2; ++k) dst[m][k] = *(const LAS bf16x8*)(lds + G_SA(b, h) + aoff + m * 2048 + k * 1024); } while (0)
; #define G_MMA(ai, bj, At, Bt) do { __builtin_amdgcn_s_setprio(1); _Pragma("unroll") for (int m = 0; m < 4; ++m) _Pragma("unroll") for (int n = 0; n < 2; ++n) _Pragma("unroll") for (int k = 0; k < 2; ++k) \
;         acc[ai][bj][m][n] = MFMA16(Bt[n][k], At[m][k], acc[ai][bj][m][n]); __builtin_amdgcn_s_setprio(0); } while (0)
; #define G_WAIT_V(n) asm volatile("s_waitcnt vmcnt(" #n ")" ::: "memory")
; #define G_WAIT_L(n) asm volatile("s_waitcnt lgkmcnt(" #n ")" ::: "memory")
; #define G_BAR __builtin_amdgcn_s_barrier()
; #define G_SCHED __builtin_amdgcn_sched_barrier(0)
; template <class Epi>
; __device__ __forceinline__ void gemm_phase(LAS unsigned char* lds, const bf16_t* Ag, const bf16_t* Btg, const int K, const int nM, const int nN, const Epi& E) {
;     ...
;         for (int t = 0; t < nt; t += 2) {
;     ...
;             G_BAR; G_WAIT_L(0); G_MMA(0, 1, At, B1); G_BAR;
;             G_LDA(At, 1, 1); G_STAGE(G_SA(1, 0), a3);
;             G_BAR; G_WAIT_L(0); G_MMA(1, 0, At, B0); G_BAR; G_SCHED;
;             G_STAGE(G_SB(1, 1), b3 + hstep);
;             G_WAIT_V(6); G_BAR; G_MMA(1, 1, At, B1); G_BAR;
	s_waitcnt lgkmcnt(0)
	s_setprio 1
	s_waitcnt lgkmcnt(0)
	v_mfma_f32_16x16x32_bf16 v[124:127], v[232:235], v[160:163], v[124:127]
	v_mfma_f32_16x16x32_bf16 v[120:123], v[240:243], v[160:163], v[120:123]
	v_mfma_f32_16x16x32_bf16 v[108:111], v[232:235], v[168:171], v[108:111]
	v_mfma_f32_16x16x32_bf16 v[104:107], v[240:243], v[168:171], v[104:107]
	v_mfma_f32_16x16x32_bf16 v[92:95], v[232:235], v[180:183], v[92:95]
	v_mfma_f32_16x16x32_bf16 v[88:91], v[240:243], v[180:183], v[88:91]
	v_mfma_f32_16x16x32_bf16 v[76:79], v[232:235], v[188:191], v[76:79]
	v_mfma_f32_16x16x32_bf16 v[72:75], v[240:243], v[188:191], v[72:75]
	v_mfma_f32_16x16x32_bf16 v[124:127], v[236:239], v[164:167], v[124:127]
	v_mfma_f32_16x16x32_bf16 v[120:123], v[244:247], v[164:167], v[120:123]
	v_mfma_f32_16x16x32_bf16 v[108:111], v[236:239], v[172:175], v[108:111]
	v_mfma_f32_16x16x32_bf16 v[104:107], v[244:247], v[172:175], v[104:107]
	v_mfma_f32_16x16x32_bf16 v[92:95], v[236:239], v[184:187], v[92:95]
	v_mfma_f32_16x16x32_bf16 v[88:91], v[244:247], v[184:187], v[88:91]
	v_mfma_f32_16x16x32_bf16 v[76:79], v[236:239], v[192:195], v[76:79]
	v_mfma_f32_16x16x32_bf16 v[72:75], v[244:247], v[192:195], v[72:75]
	s_setprio 0
	s_mov_b32 m0, s76
	s_barrier
	ds_read_b128 v[160:163], v230 offset:49152
	ds_read_b128 v[164:167], v230 offset:50176
	ds_read_b128 v[168:171], v230 offset:51200
	ds_read_b128 v[172:175], v230 offset:52224
	ds_read_b128 v[180:183], v230 offset:53248
	ds_read_b128 v[184:187], v230 offset:54272
	ds_read_b128 v[188:191], v230 offset:55296
	ds_read_b128 v[192:195], v230 offset:56320
	s_add_u32 s98, s70, 0x80
	s_addc_u32 s99, s71, 0
	global_load_lds_dwordx4 v0, s[98:99]
	s_mov_b32 m0, s77
	s_nop 0
	global_load_lds_dwordx4 v2, s[98:99]
	s_barrier
	s_waitcnt lgkmcnt(0)
	s_setprio 1
	s_waitcnt lgkmcnt(0)
	v_mfma_f32_16x16x32_bf16 v[68:71], v[144:147], v[160:163], v[68:71]
	v_mfma_f32_16x16x32_bf16 v[64:67], v[152:155], v[160:163], v[64:67]
	v_mfma_f32_16x16x32_bf16 v[52:55], v[144:147], v[168:171], v[52:55]
	v_mfma_f32_16x16x32_bf16 v[48:51], v[152:155], v[168:171], v[48:51]
	v_mfma_f32_16x16x32_bf16 v[36:39], v[144:147], v[180:183], v[36:39]
	v_mfma_f32_16x16x32_bf16 v[32:35], v[152:155], v[180:183], v[32:35]
	v_mfma_f32_16x16x32_bf16 v[20:23], v[144:147], v[188:191], v[20:23]
	v_mfma_f32_16x16x32_bf16 v[16:19], v[152:155], v[188:191], v[16:19]
	v_mfma_f32_16x16x32_bf16 v[68:71], v[148:151], v[164:167], v[68:71]
	v_mfma_f32_16x16x32_bf16 v[64:67], v[156:159], v[164:167], v[64:67]
	v_mfma_f32_16x16x32_bf16 v[52:55], v[148:151], v[172:175], v[52:55]
	v_mfma_f32_16x16x32_bf16 v[48:51], v[156:159], v[172:175], v[48:51]
	v_mfma_f32_16x16x32_bf16 v[36:39], v[148:151], v[184:187], v[36:39]
	v_mfma_f32_16x16x32_bf16 v[32:35], v[156:159], v[184:187], v[32:35]
	v_mfma_f32_16x16x32_bf16 v[20:23], v[148:151], v[192:195], v[20:23]
	v_mfma_f32_16x16x32_bf16 v[16:19], v[156:159], v[192:195], v[16:19]
	s_setprio 0
	s_barrier
	s_add_u32 s64, s68, 0x40080
	s_addc_u32 s65, s69, 0
	s_add_i32 s12, s26, s21
	s_mov_b32 m0, s12
	s_nop 0
	global_load_lds_dwordx4 v0, s[64:65]
	s_add_i32 m0, s12, 0x2000
	s_nop 0
	global_load_lds_dwordx4 v2, s[64:65]
	s_waitcnt vmcnt(6)
	s_barrier
	s_setprio 1
	v_mfma_f32_16x16x32_bf16 v[60:63], v[232:235], v[160:163], v[60:63]
	v_mfma_f32_16x16x32_bf16 v[56:59], v[240:243], v[160:163], v[56:59]
	v_mfma_f32_16x16x32_bf16 v[44:47], v[232:235], v[168:171], v[44:47]
	v_mfma_f32_16x16x32_bf16 v[40:43], v[240:243], v[168:171], v[40:43]
	v_mfma_f32_16x16x32_bf16 v[28:31], v[232:235], v[180:183], v[28:31]
	v_mfma_f32_16x16x32_bf16 v[24:27], v[240:243], v[180:183], v[24:27]
	v_mfma_f32_16x16x32_bf16 v[12:15], v[232:235], v[188:191], v[12:15]
	v_mfma_f32_16x16x32_bf16 v[8:11], v[240:243], v[188:191], v[8:11]
	v_mfma_f32_16x16x32_bf16 v[60:63], v[236:239], v[164:167], v[60:63]
	v_mfma_f32_16x16x32_bf16 v[56:59], v[244:247], v[164:167], v[56:59]
	v_mfma_f32_16x16x32_bf16 v[44:47], v[236:239], v[172:175], v[44:47]
	v_mfma_f32_16x16x32_bf16 v[40:43], v[244:247], v[172:175], v[40:43]
	v_mfma_f32_16x16x32_bf16 v[28:31], v[236:239], v[184:187], v[28:31]
	v_mfma_f32_16x16x32_bf16 v[24:27], v[244:247], v[184:187], v[24:27]
	v_mfma_f32_16x16x32_bf16 v[12:15], v[236:239], v[192:195], v[12:15]
	v_mfma_f32_16x16x32_bf16 v[8:11], v[244:247], v[192:195], v[8:11]
	s_setprio 0
	s_add_i32 s42, s42, 2
	s_add_u32 s57, s57, 0x100
	s_addc_u32 s61, s61, 0
	s_cmp_gt_u32 s42, 13
	s_mov_b64 s[64:65], s[66:67]
	s_barrier
	s_cbranch_scc1 .LBB0_157

;     __device__ __forceinline__ void prep(int pm, int par, LAS unsigned char* lds) const { if (fold) prep_rowstats(stat, pm, par, lds); }
;     __device__ __forceinline__ void prep(int pm, int par, LAS unsigned char* lds) const { if (!ident) prep_rowstats(stat, pm, par, lds); }
;     __device__ __forceinline__ void prep(int pm, int par, LAS unsigned char* lds) const { prep_rowstats(stat, pm, par, lds); }
; #define G_STAGE(bufoff, gbase) do { _Pragma("unroll") for (int _i = 0; _i < 2; ++_i) \
;         __builtin_amdgcn_global_load_lds((const unsigned*)((const char*)(gbase) + voff[_i]), (LAS unsigned*)(lds + (bufoff) + ldsw + _i * 8192), 16, 0, 0); } while (0)
; #define G_LDA(dst, b, h) do { _Pragma("unroll") for (int m = 0; m < 4; ++m) _Pragma("unroll") for (int k = 0; k < 2; ++k) dst[m][k] = *(const LAS bf16x8*)(lds + G_SA(b, h) + aoff + m * 2048 + k * 1024); } while (0)
; #define G_LDB(dst, b, h) do { _Pragma("unroll") for (int n = 0; n < 2; ++n) _Pragma("unroll") for (int k = 0; k < 2; ++k) dst[n][k] = *(const LAS bf16x8*)(lds + G_SB(b, h) + boff + n * 2048 + k * 1024); } while (0)
; #define G_WAIT_L(n) asm volatile("s_waitcnt lgkmcnt(" #n ")" ::: "memory")
; #define G_BAR __builtin_amdgcn_s_barrier()
; #define G_SCHED __builtin_amdgcn_sched_barrier(0)
; template <class Epi>
; __device__ __forceinline__ void gemm_phase(LAS unsigned char* lds, const bf16_t* Ag, const bf16_t* Btg, const int K, const int nM, const int nN, const Epi& E) {
;     ...
;         for (int t = 0; t < nt; t += 2) {
;             const bool last = (t == nt - 2);
;             const char* a1 = cA + (size_t)(t + 1) * kstep;
;             const char* a2 = last ? nA : cA + (size_t)(t + 2) * kstep; const char* b2 = last ? nB : cB + (size_t)(t + 2) * kstep;
;             const char* a3 = a2 + kstep; const char* b3 = b2 + kstep;
;             if (last && has_next && pmn != pm) E.prep(pmn, par ^ 1, lds);
;             G_LDB(B0, 0, 0); G_SCHED; G_LDA(At, 0, 0); G_STAGE(G_SA(1, 1), a1 + hstep);
;             G_WAIT_L(8); G_BAR; G_WAIT_L(0); G_MMA(0, 0, At, B0); G_BAR; G_SCHED;
;             G_LDB(B1, 0, 1); G_STAGE(G_SB(0, 0), b2);
;             G_BAR; G_WAIT_L(0); G_MMA(0, 1, At, B1); G_BAR;
;             G_LDA(At, 0, 1); G_STAGE(G_SA(0, 0), a2);
;             G_BAR; G_WAIT_L(0); G_MMA(1, 0, At, B0); G_BAR; G_SCHED;
;             G_STAGE(G_SB(0, 1), b2 + hstep);
.LBB0_744:
	s_add_u32 s58, s56, 0x100
	s_addc_u32 s59, s57, 0
	s_and_b64 s[60:61], s[60:61], exec
	s_cselect_b32 s63, s59, s47
	s_cselect_b32 s62, s58, s46
	s_cselect_b32 s61, s78, s15
	s_cselect_b32 s60, s77, s49
	s_add_i32 s12, 0, 0x10000
	v_add_u32_e32 v152, s12, v165
	ds_read_b128 v[140:143], v152
	ds_read_b128 v[144:147], v152 offset:1024
	ds_read_b128 v[148:151], v152 offset:2048
	ds_read_b128 v[152:155], v152 offset:3072
	s_add_i32 m0, s66, 0xc000
	ds_read_b128 v[156:159], v174
	ds_read_b128 v[160:163], v174 offset:1024
	ds_read_b128 v[180:183], v174 offset:2048
	ds_read_b128 v[184:187], v174 offset:3072
	ds_read_b128 v[188:191], v174 offset:4096
	ds_read_b128 v[192:195], v174 offset:5120
	ds_read_b128 v[222:225], v174 offset:6144
	global_load_lds_dwordx4 v138, s[56:57]
	s_add_i32 m0, s66, 0xe000
	ds_read_b128 v[226:229], v174 offset:7168
	global_load_lds_dwordx4 v136, s[56:57]
	s_waitcnt lgkmcnt(8)
	s_barrier
	s_waitcnt lgkmcnt(0)
	s_setprio 1
	s_waitcnt lgkmcnt(0)
	v_mfma_f32_16x16x32_bf16 v[132:135], v[140:143], v[156:159], v[132:135]
	v_mfma_f32_16x16x32_bf16 v[128:131], v[148:151], v[156:159], v[128:131]
	v_mfma_f32_16x16x32_bf16 v[116:119], v[140:143], v[180:183], v[116:119]
	v_mfma_f32_16x16x32_bf16 v[112:115], v[148:151], v[180:183], v[112:115]
	v_mfma_f32_16x16x32_bf16 v[100:103], v[140:143], v[188:191], v[100:103]
	v_mfma_f32_16x16x32_bf16 v[96:99], v[148:151], v[188:191], v[96:99]
	v_mfma_f32_16x16x32_bf16 v[84:87], v[140:143], v[222:225], v[84:87]
	v_mfma_f32_16x16x32_bf16 v[80:83], v[148:151], v[222:225], v[80:83]
	v_mfma_f32_16x16x32_bf16 v[132:135], v[144:147], v[160:163], v[132:135]
	v_mfma_f32_16x16x32_bf16 v[128:131], v[152:155], v[160:163], v[128:131]
	v_mfma_f32_16x16x32_bf16 v[116:119], v[144:147], v[184:187], v[116:119]
	v_mfma_f32_16x16x32_bf16 v[112:115], v[152:155], v[184:187], v[112:115]
	v_mfma_f32_16x16x32_bf16 v[100:103], v[144:147], v[192:195], v[100:103]
	v_mfma_f32_16x16x32_bf16 v[96:99], v[152:155], v[192:195], v[96:99]
	v_mfma_f32_16x16x32_bf16 v[84:87], v[144:147], v[226:229], v[84:87]
	v_mfma_f32_16x16x32_bf16 v[80:83], v[152:155], v[226:229], v[80:83]
	s_setprio 0
	s_barrier
	s_add_i32 s26, 0, 0x14000
	s_add_i32 s12, s12, s65
	v_add_u32_e32 v175, s26, v165
	s_mov_b32 m0, s12
	ds_read_b128 v[230:233], v175
	ds_read_b128 v[234:237], v175 offset:1024
	ds_read_b128 v[238:241], v175 offset:2048
	global_load_lds_dwordx4 v0, s[60:61]
	s_add_i32 m0, s12, 0x2000
	ds_read_b128 v[242:245], v175 offset:3072
	global_load_lds_dwordx4 v2, s[60:61]
	s_barrier
	s_waitcnt lgkmcnt(0)
	s_setprio 1
	s_waitcnt lgkmcnt(0)
	v_mfma_f32_16x16x32_bf16 v[124:127], v[230:233], v[156:159], v[124:127]
	v_mfma_f32_16x16x32_bf16 v[120:123], v[238:241], v[156:159], v[120:123]
	v_mfma_f32_16x16x32_bf16 v[108:111], v[230:233], v[180:183], v[108:111]
	v_mfma_f32_16x16x32_bf16 v[104:107], v[238:241], v[180:183], v[104:107]
	v_mfma_f32_16x16x32_bf16 v[92:95], v[230:233], v[188:191], v[92:95]
	v_mfma_f32_16x16x32_bf16 v[88:91], v[238:241], v[188:191], v[88:91]
	v_mfma_f32_16x16x32_bf16 v[76:79], v[230:233], v[222:225], v[76:79]
	v_mfma_f32_16x16x32_bf16 v[72:75], v[238:241], v[222:225], v[72:75]
	v_mfma_f32_16x16x32_bf16 v[124:127], v[234:237], v[160:163], v[124:127]
	v_mfma_f32_16x16x32_bf16 v[120:123], v[242:245], v[160:163], v[120:123]
	v_mfma_f32_16x16x32_bf16 v[108:111], v[234:237], v[184:187], v[108:111]
	v_mfma_f32_16x16x32_bf16 v[104:107], v[242:245], v[184:187], v[104:107]
	v_mfma_f32_16x16x32_bf16 v[92:95], v[234:237], v[192:195], v[92:95]
	v_mfma_f32_16x16x32_bf16 v[88:91], v[242:245], v[192:195], v[88:91]
	v_mfma_f32_16x16x32_bf16 v[76:79], v[234:237], v[226:229], v[76:79]
	v_mfma_f32_16x16x32_bf16 v[72:75], v[242:245], v[226:229], v[72:75]
	s_setprio 0
	s_mov_b32 m0, s66
	s_barrier
	ds_read_b128 v[156:159], v174 offset:16384
	ds_read_b128 v[160:163], v174 offset:17408
	ds_read_b128 v[180:183], v174 offset:18432
	ds_read_b128 v[184:187], v174 offset:19456
	ds_read_b128 v[188:191], v174 offset:20480
	ds_read_b128 v[192:195], v174 offset:21504
	ds_read_b128 v[222:225], v174 offset:22528
	global_load_lds_dwordx4 v0, s[62:63]
	s_mov_b32 m0, s67
	ds_read_b128 v[226:229], v174 offset:23552
	global_load_lds_dwordx4 v2, s[62:63]
	s_barrier
	s_waitcnt lgkmcnt(0)
	s_setprio 1
	s_waitcnt lgkmcnt(0)
	v_mfma_f32_16x16x32_bf16 v[68:71], v[140:143], v[156:159], v[68:71]
	v_mfma_f32_16x16x32_bf16 v[64:67], v[148:151], v[156:159], v[64:67]
	v_mfma_f32_16x16x32_bf16 v[52:55], v[140:143], v[180:183], v[52:55]
	v_mfma_f32_16x16x32_bf16 v[48:51], v[148:151], v[180:183], v[48:51]
	v_mfma_f32_16x16x32_bf16 v[36:39], v[140:143], v[188:191], v[36:39]
	v_mfma_f32_16x16x32_bf16 v[32:35], v[148:151], v[188:191], v[32:35]
	v_mfma_f32_16x16x32_bf16 v[20:23], v[140:143], v[222:225], v[20:23]
	v_mfma_f32_16x16x32_bf16 v[16:19], v[148:151], v[222:225], v[16:19]
	v_mfma_f32_16x16x32_bf16 v[68:71], v[144:147], v[160:163], v[68:71]
	v_mfma_f32_16x16x32_bf16 v[64:67], v[152:155], v[160:163], v[64:67]
	v_mfma_f32_16x16x32_bf16 v[52:55], v[144:147], v[184:187], v[52:55]
	v_mfma_f32_16x16x32_bf16 v[48:51], v[152:155], v[184:187], v[48:51]
	v_mfma_f32_16x16x32_bf16 v[36:39], v[144:147], v[192:195], v[36:39]
	v_mfma_f32_16x16x32_bf16 v[32:35], v[152:155], v[192:195], v[32:35]
	v_mfma_f32_16x16x32_bf16 v[20:23], v[144:147], v[226:229], v[20:23]
	v_mfma_f32_16x16x32_bf16 v[16:19], v[152:155], v[226:229], v[16:19]
	s_setprio 0
	s_barrier
	s_add_u32 s56, s60, 0x100000
	s_addc_u32 s57, s61, 0
	s_add_i32 s12, s26, s65
	s_mov_b32 m0, s12
	s_nop 0
	global_load_lds_dwordx4 v0, s[56:57]
	s_add_i32 m0, s12, 0x2000
	s_nop 0
	global_load_lds_dwordx4 v2, s[56:57]
	s_waitcnt vmcnt(6)
	s_barrier
; #define G_STAGE(bufoff, gbase) do { _Pragma("unroll") for (int _i = 0; _i < 2; ++_i) \
;         __builtin_amdgcn_global_load_lds((const unsigned*)((const char*)(gbase) + voff[_i]), (LAS unsigned*)(lds + (bufoff) + ldsw + _i * 8192), 16, 0, 0); } while (0)
; #define G_LDA(dst, b, h) do { _Pragma("unroll") for (int m = 0; m < 4; ++m) _Pragma("unroll") for (int k = 0; k < 2; ++k) dst[m][k] = *(const LAS bf16x8*)(lds + G_SA(b, h) + aoff + m * 2048 + k * 1024); } while (0)
; #define G_LDB(dst, b, h) do { _Pragma("unroll") for (int n = 0; n < 2; ++n) _Pragma("unroll") for (int k = 0; k < 2; ++k) dst[n][k] = *(const LAS bf16x8*)(lds + G_SB(b, h) + boff + n * 2048 + k * 1024); } while (0)
; #define G_MMA(ai, bj, At, Bt) do { __builtin_amdgcn_s_setprio(1); _Pragma("unroll") for (int m = 0; m < 4; ++m) _Pragma("unroll") for (int n = 0; n < 2; ++n) _Pragma("unroll") for (int k = 0; k < 2; ++k) \
;         acc[ai][bj][m][n] = MFMA16(Bt[n][k], At[m][k], acc[ai][bj][m][n]); __builtin_amdgcn_s_setprio(0); } while (0)
; #define G_WAIT_V(n) asm volatile("s_waitcnt vmcnt(" #n ")" ::: "memory")
; #define G_WAIT_L(n) asm volatile("s_waitcnt lgkmcnt(" #n ")" ::: "memory")
; #define G_BAR __builtin_amdgcn_s_barrier()
; #define G_SCHED __builtin_amdgcn_sched_barrier(0)
; template <class Epi>
; __device__ __forceinline__ void gemm_phase(LAS unsigned char* lds, const bf16_t* Ag, const bf16_t* Btg, const int K, const int nM, const int nN, const Epi& E) {
;     ...
;             G_WAIT_V(6); G_BAR; G_MMA(1, 1, At, B1); G_BAR;
;             G_LDB(B0, 1, 0); G_SCHED; G_LDA(At, 1, 0); G_STAGE(G_SA(0, 1), a2 + hstep);
;             G_WAIT_L(8); G_BAR; G_WAIT_L(0); G_MMA(0, 0, At, B0); G_BAR; G_SCHED;
;             G_LDB(B1, 1, 1); G_STAGE(G_SB(1, 0), b3);
	s_setprio 1
	v_mfma_f32_16x16x32_bf16 v[60:63], v[230:233], v[156:159], v[60:63]
	v_mfma_f32_16x16x32_bf16 v[56:59], v[238:241], v[156:159], v[56:59]
	v_mfma_f32_16x16x32_bf16 v[44:47], v[230:233], v[180:183], v[44:47]
	v_mfma_f32_16x16x32_bf16 v[40:43], v[238:241], v[180:183], v[40:43]
	v_mfma_f32_16x16x32_bf16 v[28:31], v[230:233], v[188:191], v[28:31]
	v_mfma_f32_16x16x32_bf16 v[24:27], v[238:241], v[188:191], v[24:27]
	v_mfma_f32_16x16x32_bf16 v[12:15], v[230:233], v[222:225], v[12:15]
	v_mfma_f32_16x16x32_bf16 v[8:11], v[238:241], v[222:225], v[8:11]
	v_mfma_f32_16x16x32_bf16 v[60:63], v[234:237], v[160:163], v[60:63]
	v_mfma_f32_16x16x32_bf16 v[56:59], v[242:245], v[160:163], v[56:59]
	v_mfma_f32_16x16x32_bf16 v[44:47], v[234:237], v[184:187], v[44:47]
	v_mfma_f32_16x16x32_bf16 v[40:43], v[242:245], v[184:187], v[40:43]
	v_mfma_f32_16x16x32_bf16 v[28:31], v[234:237], v[192:195], v[28:31]
	v_mfma_f32_16x16x32_bf16 v[24:27], v[242:245], v[192:195], v[24:27]
	v_mfma_f32_16x16x32_bf16 v[12:15], v[234:237], v[226:229], v[12:15]
	v_mfma_f32_16x16x32_bf16 v[8:11], v[242:245], v[226:229], v[8:11]
	s_setprio 0
	s_add_i32 s12, 0, 0x18000
	v_add_u32_e32 v152, s12, v165
	s_barrier
	ds_read_b128 v[140:143], v152
	ds_read_b128 v[144:147], v152 offset:1024
	ds_read_b128 v[148:151], v152 offset:2048
	ds_read_b128 v[152:155], v152 offset:3072
	s_add_u32 s56, s62, 0x100000
	s_addc_u32 s57, s63, 0
	s_mov_b32 m0, s68
	ds_read_b128 v[156:159], v174 offset:32768
	ds_read_b128 v[160:163], v174 offset:33792
	ds_read_b128 v[180:183], v174 offset:34816
	ds_read_b128 v[184:187], v174 offset:35840
	ds_read_b128 v[188:191], v174 offset:36864
	ds_read_b128 v[192:195], v174 offset:37888
	ds_read_b128 v[222:225], v174 offset:38912
	global_load_lds_dwordx4 v0, s[56:57]
	s_mov_b32 m0, s69
	ds_read_b128 v[226:229], v174 offset:39936
	global_load_lds_dwordx4 v2, s[56:57]
	s_waitcnt lgkmcnt(8)
	s_barrier
	s_waitcnt lgkmcnt(0)
	s_setprio 1
	s_waitcnt lgkmcnt(0)
	v_mfma_f32_16x16x32_bf16 v[132:135], v[140:143], v[156:159], v[132:135]
	v_mfma_f32_16x16x32_bf16 v[128:131], v[148:151], v[156:159], v[128:131]
	v_mfma_f32_16x16x32_bf16 v[116:119], v[140:143], v[180:183], v[116:119]
	v_mfma_f32_16x16x32_bf16 v[112:115], v[148:151], v[180:183], v[112:115]
	v_mfma_f32_16x16x32_bf16 v[100:103], v[140:143], v[188:191], v[100:103]
	v_mfma_f32_16x16x32_bf16 v[96:99], v[148:151], v[188:191], v[96:99]
	v_mfma_f32_16x16x32_bf16 v[84:87], v[140:143], v[222:225], v[84:87]
	v_mfma_f32_16x16x32_bf16 v[80:83], v[148:151], v[222:225], v[80:83]
	v_mfma_f32_16x16x32_bf16 v[132:135], v[144:147], v[160:163], v[132:135]
	v_mfma_f32_16x16x32_bf16 v[128:131], v[152:155], v[160:163], v[128:131]
	v_mfma_f32_16x16x32_bf16 v[116:119], v[144:147], v[184:187], v[116:119]
	v_mfma_f32_16x16x32_bf16 v[112:115], v[152:155], v[184:187], v[112:115]
	v_mfma_f32_16x16x32_bf16 v[100:103], v[144:147], v[192:195], v[100:103]
	v_mfma_f32_16x16x32_bf16 v[96:99], v[152:155], v[192:195], v[96:99]
	v_mfma_f32_16x16x32_bf16 v[84:87], v[144:147], v[226:229], v[84:87]
	v_mfma_f32_16x16x32_bf16 v[80:83], v[152:155], v[226:229], v[80:83]
	s_setprio 0
	s_barrier
	s_add_i32 s26, 0, 0x1c000
	s_add_i32 s12, s12, s65
	v_add_u32_e32 v175, s26, v165
	s_mov_b32 m0, s12
	ds_read_b128 v[230:233], v175
	ds_read_b128 v[234:237], v175 offset:1024
	ds_read_b128 v[238:241], v175 offset:2048
	ds_read_b128 v[242:245], v175 offset:3072
	s_add_u32 s98, s60, 0x80
	s_addc_u32 s99, s61, 0
	global_load_lds_dwordx4 v0, s[98:99]
	s_add_i32 m0, s12, 0x2000
	s_nop 0
	global_load_lds_dwordx4 v2, s[98:99]
	s_barrier
; #define G_STAGE(bufoff, gbase) do { _Pragma("unroll") for (int _i = 0; _i < 2; ++_i) \
;         __builtin_amdgcn_global_load_lds((const unsigned*)((const char*)(gbase) + voff[_i]), (LAS unsigned*)(lds + (bufoff) + ldsw + _i * 8192), 16, 0, 0); } while (0)
; #define G_LDA(dst, b, h) do { _Pragma("unroll") for (int m = 0; m < 4; ++m) _Pragma("unroll") for (int k = 0; k < 2; ++k) dst[m][k] = *(const LAS bf16x8*)(lds + G_SA(b, h) + aoff + m * 2048 + k * 1024); } while (0)
; #define G_MMA(ai, bj, At, Bt) do { __builtin_amdgcn_s_setprio(1); _Pragma("unroll") for (int m = 0; m < 4; ++m) _Pragma("unroll") for (int n = 0; n < 2; ++n) _Pragma("unroll") for (int k = 0; k < 2; ++k) \
;         acc[ai][bj][m][n] = MFMA16(Bt[n][k], At[m][k], acc[ai][bj][m][n]); __builtin_amdgcn_s_setprio(0); } while (0)
; #define G_WAIT_V(n) asm volatile("s_waitcnt vmcnt(" #n ")" ::: "memory")
; #define G_WAIT_L(n) asm volatile("s_waitcnt lgkmcnt(" #n ")" ::: "memory")
; #define G_BAR __builtin_amdgcn_s_barrier()
; #define G_SCHED __builtin_amdgcn_sched_barrier(0)
; template <class Epi>
; __device__ __forceinline__ void gemm_phase(LAS unsigned char* lds, const bf16_t* Ag, const bf16_t* Btg, const int K, const int nM, const int nN, const Epi& E) {
;     ...
;         for (int t = 0; t < nt; t += 2) {
;     ...
;             G_BAR; G_WAIT_L(0); G_MMA(0, 1, At, B1); G_BAR;
;             G_LDA(At, 1, 1); G_STAGE(G_SA(1, 0), a3);
;             G_BAR; G_WAIT_L(0); G_MMA(1, 0, At, B0); G_BAR; G_SCHED;
;             G_STAGE(G_SB(1, 1), b3 + hstep);
;             G_WAIT_V(6); G_BAR; G_MMA(1, 1, At, B1); G_BAR;
	s_waitcnt lgkmcnt(0)
	s_setprio 1
	s_waitcnt lgkmcnt(0)
	v_mfma_f32_16x16x32_bf16 v[124:127], v[230:233], v[156:159], v[124:127]
	v_mfma_f32_16x16x32_bf16 v[120:123], v[238:241], v[156:159], v[120:123]
	v_mfma_f32_16x16x32_bf16 v[108:111], v[230:233], v[180:183], v[108:111]
	v_mfma_f32_16x16x32_bf16 v[104:107], v[238:241], v[180:183], v[104:107]
	v_mfma_f32_16x16x32_bf16 v[92:95], v[230:233], v[188:191], v[92:95]
	v_mfma_f32_16x16x32_bf16 v[88:91], v[238:241], v[188:191], v[88:91]
	v_mfma_f32_16x16x32_bf16 v[76:79], v[230:233], v[222:225], v[76:79]
	v_mfma_f32_16x16x32_bf16 v[72:75], v[238:241], v[222:225], v[72:75]
	v_mfma_f32_16x16x32_bf16 v[124:127], v[234:237], v[160:163], v[124:127]
	v_mfma_f32_16x16x32_bf16 v[120:123], v[242:245], v[160:163], v[120:123]
	v_mfma_f32_16x16x32_bf16 v[108:111], v[234:237], v[184:187], v[108:111]
	v_mfma_f32_16x16x32_bf16 v[104:107], v[242:245], v[184:187], v[104:107]
	v_mfma_f32_16x16x32_bf16 v[92:95], v[234:237], v[192:195], v[92:95]
	v_mfma_f32_16x16x32_bf16 v[88:91], v[242:245], v[192:195], v[88:91]
	v_mfma_f32_16x16x32_bf16 v[76:79], v[234:237], v[226:229], v[76:79]
	v_mfma_f32_16x16x32_bf16 v[72:75], v[242:245], v[226:229], v[72:75]
	s_setprio 0
	s_mov_b32 m0, s70
	s_barrier
	ds_read_b128 v[156:159], v174 offset:49152
	ds_read_b128 v[160:163], v174 offset:50176
	ds_read_b128 v[180:183], v174 offset:51200
	ds_read_b128 v[184:187], v174 offset:52224
	ds_read_b128 v[188:191], v174 offset:53248
	ds_read_b128 v[192:195], v174 offset:54272
	ds_read_b128 v[222:225], v174 offset:55296
	ds_read_b128 v[226:229], v174 offset:56320
	s_add_u32 s98, s62, 0x80
	s_addc_u32 s99, s63, 0
	global_load_lds_dwordx4 v0, s[98:99]
	s_mov_b32 m0, s71
	s_nop 0
	global_load_lds_dwordx4 v2, s[98:99]
	s_barrier
	s_waitcnt lgkmcnt(0)
	s_setprio 1
	s_waitcnt lgkmcnt(0)
	v_mfma_f32_16x16x32_bf16 v[68:71], v[140:143], v[156:159], v[68:71]
	v_mfma_f32_16x16x32_bf16 v[64:67], v[148:151], v[156:159], v[64:67]
	v_mfma_f32_16x16x32_bf16 v[52:55], v[140:143], v[180:183], v[52:55]
	v_mfma_f32_16x16x32_bf16 v[48:51], v[148:151], v[180:183], v[48:51]
	v_mfma_f32_16x16x32_bf16 v[36:39], v[140:143], v[188:191], v[36:39]
	v_mfma_f32_16x16x32_bf16 v[32:35], v[148:151], v[188:191], v[32:35]
	v_mfma_f32_16x16x32_bf16 v[20:23], v[140:143], v[222:225], v[20:23]
	v_mfma_f32_16x16x32_bf16 v[16:19], v[148:151], v[222:225], v[16:19]
	v_mfma_f32_16x16x32_bf16 v[68:71], v[144:147], v[160:163], v[68:71]
	v_mfma_f32_16x16x32_bf16 v[64:67], v[152:155], v[160:163], v[64:67]
	v_mfma_f32_16x16x32_bf16 v[52:55], v[144:147], v[184:187], v[52:55]
	v_mfma_f32_16x16x32_bf16 v[48:51], v[152:155], v[184:187], v[48:51]
	v_mfma_f32_16x16x32_bf16 v[36:39], v[144:147], v[192:195], v[36:39]
	v_mfma_f32_16x16x32_bf16 v[32:35], v[152:155], v[192:195], v[32:35]
	v_mfma_f32_16x16x32_bf16 v[20:23], v[144:147], v[226:229], v[20:23]
	v_mfma_f32_16x16x32_bf16 v[16:19], v[152:155], v[226:229], v[16:19]
	s_setprio 0
	s_barrier
	s_add_u32 s56, s60, 0x100080
	s_addc_u32 s57, s61, 0
	s_add_i32 s12, s26, s65
	s_mov_b32 m0, s12
	s_nop 0
	global_load_lds_dwordx4 v0, s[56:57]
	s_add_i32 m0, s12, 0x2000
	s_nop 0
	global_load_lds_dwordx4 v2, s[56:57]
	s_waitcnt vmcnt(6)
	s_barrier
	s_setprio 1
	v_mfma_f32_16x16x32_bf16 v[60:63], v[230:233], v[156:159], v[60:63]
	v_mfma_f32_16x16x32_bf16 v[56:59], v[238:241], v[156:159], v[56:59]
	v_mfma_f32_16x16x32_bf16 v[44:47], v[230:233], v[180:183], v[44:47]
	v_mfma_f32_16x16x32_bf16 v[40:43], v[238:241], v[180:183], v[40:43]
	v_mfma_f32_16x16x32_bf16 v[28:31], v[230:233], v[188:191], v[28:31]
	v_mfma_f32_16x16x32_bf16 v[24:27], v[238:241], v[188:191], v[24:27]
	v_mfma_f32_16x16x32_bf16 v[12:15], v[230:233], v[222:225], v[12:15]
	v_mfma_f32_16x16x32_bf16 v[8:11], v[238:241], v[222:225], v[8:11]
	v_mfma_f32_16x16x32_bf16 v[60:63], v[234:237], v[160:163], v[60:63]
	v_mfma_f32_16x16x32_bf16 v[56:59], v[242:245], v[160:163], v[56:59]
	v_mfma_f32_16x16x32_bf16 v[44:47], v[234:237], v[184:187], v[44:47]
	v_mfma_f32_16x16x32_bf16 v[40:43], v[242:245], v[184:187], v[40:43]
	v_mfma_f32_16x16x32_bf16 v[28:31], v[234:237], v[192:195], v[28:31]
	v_mfma_f32_16x16x32_bf16 v[24:27], v[242:245], v[192:195], v[24:27]
	v_mfma_f32_16x16x32_bf16 v[12:15], v[234:237], v[226:229], v[12:15]
	v_mfma_f32_16x16x32_bf16 v[8:11], v[242:245], v[226:229], v[8:11]
	s_setprio 0
	s_add_i32 s79, s79, 2
	s_add_u32 s77, s77, 0x100
	s_addc_u32 s78, s78, 0
	s_cmp_gt_u32 s79, 61
	s_mov_b64 s[56:57], s[58:59]
	s_barrier
	s_cbranch_scc1 .LBB0_748

;     __device__ __forceinline__ void prep(int pm, int par, LAS unsigned char* lds) const { if (fold) prep_rowstats(stat, pm, par, lds); }
;     __device__ __forceinline__ void prep(int pm, int par, LAS unsigned char* lds) const { if (!ident) prep_rowstats(stat, pm, par, lds); }
;     __device__ __forceinline__ void prep(int pm, int par, LAS unsigned char* lds) const { prep_rowstats(stat, pm, par, lds); }
; #define G_STAGE(bufoff, gbase) do { _Pragma("unroll") for (int _i = 0; _i < 2; ++_i) \
;         __builtin_amdgcn_global_load_lds((const unsigned*)((const char*)(gbase) + voff[_i]), (LAS unsigned*)(lds + (bufoff) + ldsw + _i * 8192), 16, 0, 0); } while (0)
; #define G_LDA(dst, b, h) do { _Pragma("unroll") for (int m = 0; m < 4; ++m) _Pragma("unroll") for (int k = 0; k < 2; ++k) dst[m][k] = *(const LAS bf16x8*)(lds + G_SA(b, h) + aoff + m * 2048 + k * 1024); } while (0)
; #define G_LDB(dst, b, h) do { _Pragma("unroll") for (int n = 0; n < 2; ++n) _Pragma("unroll") for (int k = 0; k < 2; ++k) dst[n][k] = *(const LAS bf16x8*)(lds + G_SB(b, h) + boff + n * 2048 + k * 1024); } while (0)
; #define G_WAIT_L(n) asm volatile("s_waitcnt lgkmcnt(" #n ")" ::: "memory")
; #define G_BAR __builtin_amdgcn_s_barrier()
; #define G_SCHED __builtin_amdgcn_sched_barrier(0)
; template <class Epi>
; __device__ __forceinline__ void gemm_phase(LAS unsigned char* lds, const bf16_t* Ag, const bf16_t* Btg, const int K, const int nM, const int nN, const Epi& E) {
;     ...
;         for (int t = 0; t < nt; t += 2) {
;             const bool last = (t == nt - 2);
;             const char* a1 = cA + (size_t)(t + 1) * kstep;
;             const char* a2 = last ? nA : cA + (size_t)(t + 2) * kstep; const char* b2 = last ? nB : cB + (size_t)(t + 2) * kstep;
;             const char* a3 = a2 + kstep; const char* b3 = b2 + kstep;
;             if (last && has_next && pmn != pm) E.prep(pmn, par ^ 1, lds);
;             G_LDB(B0, 0, 0); G_SCHED; G_LDA(At, 0, 0); G_STAGE(G_SA(1, 1), a1 + hstep);
;             G_WAIT_L(8); G_BAR; G_WAIT_L(0); G_MMA(0, 0, At, B0); G_BAR; G_SCHED;
;             G_LDB(B1, 0, 1); G_STAGE(G_SB(0, 0), b2);
;             G_BAR; G_WAIT_L(0); G_MMA(0, 1, At, B1); G_BAR;
;             G_LDA(At, 0, 1); G_STAGE(G_SA(0, 0), a2);
;             G_BAR; G_WAIT_L(0); G_MMA(1, 0, At, B0); G_BAR; G_SCHED;
;             G_STAGE(G_SB(0, 1), b2 + hstep);
.LBB0_848:
	s_add_u32 s26, s50, 0xfffc0080
	s_addc_u32 s54, s51, -1
	s_and_b64 s[52:53], s[52:53], exec
	s_cselect_b32 s55, s54, s25
	s_cselect_b32 s54, s26, s24
	s_cselect_b32 s53, s71, s14
	s_cselect_b32 s52, s70, s15
	s_add_i32 s26, 0, 0x10000
	v_add_u32_e32 v129, s26, v179
	ds_read_b128 v[130:133], v129
	ds_read_b128 v[134:137], v129 offset:1024
	ds_read_b128 v[144:147], v129 offset:2048
	ds_read_b128 v[148:151], v129 offset:3072
	s_add_i32 m0, s60, 0xc000
	ds_read_b128 v[156:159], v222
	ds_read_b128 v[160:163], v222 offset:1024
	ds_read_b128 v[164:167], v222 offset:2048
	ds_read_b128 v[180:183], v222 offset:3072
	ds_read_b128 v[184:187], v222 offset:4096
	ds_read_b128 v[224:227], v222 offset:5120
	ds_read_b128 v[228:231], v222 offset:6144
	global_load_lds_dwordx4 v170, s[50:51]
	s_add_i32 m0, s60, 0xe000
	ds_read_b128 v[232:235], v222 offset:7168
	global_load_lds_dwordx4 v168, s[50:51]
	s_waitcnt lgkmcnt(8)
	s_barrier
	s_waitcnt lgkmcnt(0)
	s_setprio 1
	s_waitcnt lgkmcnt(0)
	v_mfma_f32_16x16x32_bf16 v[152:155], v[130:133], v[156:159], v[152:155]
	v_mfma_f32_16x16x32_bf16 v[138:141], v[144:147], v[156:159], v[140:143]
	v_mfma_f32_16x16x32_bf16 v[116:119], v[130:133], v[164:167], v[116:119]
	v_mfma_f32_16x16x32_bf16 v[112:115], v[144:147], v[164:167], v[112:115]
	v_mfma_f32_16x16x32_bf16 v[100:103], v[130:133], v[184:187], v[100:103]
	v_mfma_f32_16x16x32_bf16 v[96:99], v[144:147], v[184:187], v[96:99]
	v_mfma_f32_16x16x32_bf16 v[84:87], v[130:133], v[228:231], v[84:87]
	v_mfma_f32_16x16x32_bf16 v[80:83], v[144:147], v[228:231], v[80:83]
	v_mfma_f32_16x16x32_bf16 v[152:155], v[134:137], v[160:163], v[152:155]
	v_mfma_f32_16x16x32_bf16 v[138:141], v[148:151], v[160:163], v[138:141]
	v_mfma_f32_16x16x32_bf16 v[116:119], v[134:137], v[180:183], v[116:119]
	v_mfma_f32_16x16x32_bf16 v[112:115], v[148:151], v[180:183], v[112:115]
	v_mfma_f32_16x16x32_bf16 v[100:103], v[134:137], v[224:227], v[100:103]
	v_mfma_f32_16x16x32_bf16 v[96:99], v[148:151], v[224:227], v[96:99]
	v_mfma_f32_16x16x32_bf16 v[84:87], v[134:137], v[232:235], v[84:87]
	v_mfma_f32_16x16x32_bf16 v[80:83], v[148:151], v[232:235], v[80:83]
	s_setprio 0
	s_barrier
	s_add_i32 s73, 0, 0x14000
	s_add_i32 s26, s26, s59
	v_add_u32_e32 v129, s73, v179
	s_mov_b32 m0, s26
	ds_read_b128 v[236:239], v129
	ds_read_b128 v[240:243], v129 offset:1024
	ds_read_b128 v[244:247], v129 offset:2048
	global_load_lds_dwordx4 v0, s[52:53]
	s_add_i32 m0, s26, 0x2000
	ds_read_b128 v[248:251], v129 offset:3072
	global_load_lds_dwordx4 v2, s[52:53]
	s_barrier
	s_waitcnt lgkmcnt(0)
	s_setprio 1
	s_waitcnt lgkmcnt(0)
	v_mfma_f32_16x16x32_bf16 v[124:127], v[236:239], v[156:159], v[124:127]
	v_mfma_f32_16x16x32_bf16 v[120:123], v[244:247], v[156:159], v[120:123]
	v_mfma_f32_16x16x32_bf16 v[108:111], v[236:239], v[164:167], v[108:111]
	v_mfma_f32_16x16x32_bf16 v[104:107], v[244:247], v[164:167], v[104:107]
	v_mfma_f32_16x16x32_bf16 v[92:95], v[236:239], v[184:187], v[92:95]
	v_mfma_f32_16x16x32_bf16 v[88:91], v[244:247], v[184:187], v[88:91]
	v_mfma_f32_16x16x32_bf16 v[76:79], v[236:239], v[228:231], v[76:79]
	v_mfma_f32_16x16x32_bf16 v[72:75], v[244:247], v[228:231], v[72:75]
	v_mfma_f32_16x16x32_bf16 v[124:127], v[240:243], v[160:163], v[124:127]
	v_mfma_f32_16x16x32_bf16 v[120:123], v[248:251], v[160:163], v[120:123]
	v_mfma_f32_16x16x32_bf16 v[108:111], v[240:243], v[180:183], v[108:111]
	v_mfma_f32_16x16x32_bf16 v[104:107], v[248:251], v[180:183], v[104:107]
	v_mfma_f32_16x16x32_bf16 v[92:95], v[240:243], v[224:227], v[92:95]
	v_mfma_f32_16x16x32_bf16 v[88:91], v[248:251], v[224:227], v[88:91]
	v_mfma_f32_16x16x32_bf16 v[76:79], v[240:243], v[232:235], v[76:79]
	v_mfma_f32_16x16x32_bf16 v[72:75], v[248:251], v[232:235], v[72:75]
	s_setprio 0
	s_mov_b32 m0, s60
	s_add_u32 s76, s54, 0x80
	s_addc_u32 s77, s55, 0
	s_barrier
	ds_read_b128 v[156:159], v222 offset:16384
	ds_read_b128 v[160:163], v222 offset:17408
	ds_read_b128 v[164:167], v222 offset:18432
	ds_read_b128 v[180:183], v222 offset:19456
	ds_read_b128 v[184:187], v222 offset:20480
	ds_read_b128 v[224:227], v222 offset:21504
	ds_read_b128 v[228:231], v222 offset:22528
	ds_read_b128 v[232:235], v222 offset:23552
	global_load_lds_dwordx4 v0, s[54:55]
	s_add_u32 s76, s54, 0x80
	s_mov_b32 m0, s61
	s_addc_u32 s77, s55, 0
	global_load_lds_dwordx4 v2, s[54:55]
	s_barrier
	s_waitcnt lgkmcnt(0)
	s_setprio 1
	s_waitcnt lgkmcnt(0)
	v_mfma_f32_16x16x32_bf16 v[60:63], v[130:133], v[156:159], v[60:63]
	v_mfma_f32_16x16x32_bf16 v[56:59], v[144:147], v[156:159], v[56:59]
	v_mfma_f32_16x16x32_bf16 v[44:47], v[130:133], v[164:167], v[44:47]
	v_mfma_f32_16x16x32_bf16 v[40:43], v[144:147], v[164:167], v[40:43]
	v_mfma_f32_16x16x32_bf16 v[28:31], v[130:133], v[184:187], v[28:31]
	v_mfma_f32_16x16x32_bf16 v[24:27], v[144:147], v[184:187], v[24:27]
	v_mfma_f32_16x16x32_bf16 v[12:15], v[130:133], v[228:231], v[12:15]
	v_mfma_f32_16x16x32_bf16 v[8:11], v[144:147], v[228:231], v[8:11]
	v_mfma_f32_16x16x32_bf16 v[60:63], v[134:137], v[160:163], v[60:63]
	v_mfma_f32_16x16x32_bf16 v[56:59], v[148:151], v[160:163], v[56:59]
	v_mfma_f32_16x16x32_bf16 v[44:47], v[134:137], v[180:183], v[44:47]
	v_mfma_f32_16x16x32_bf16 v[40:43], v[148:151], v[180:183], v[40:43]
	v_mfma_f32_16x16x32_bf16 v[28:31], v[134:137], v[224:227], v[28:31]
	v_mfma_f32_16x16x32_bf16 v[24:27], v[148:151], v[224:227], v[24:27]
	v_mfma_f32_16x16x32_bf16 v[12:15], v[134:137], v[232:235], v[12:15]
	v_mfma_f32_16x16x32_bf16 v[8:11], v[148:151], v[232:235], v[8:11]
	s_setprio 0
	s_barrier
	s_add_u32 s74, s52, 0x40000
	s_addc_u32 s75, s53, 0
	s_add_i32 s26, s73, s59
	s_mov_b32 m0, s26
	s_nop 0
	global_load_lds_dwordx4 v0, s[74:75]
	s_add_i32 m0, s26, 0x2000
	s_nop 0
	global_load_lds_dwordx4 v2, s[74:75]
	s_waitcnt vmcnt(6)
	s_barrier
; #define G_STAGE(bufoff, gbase) do { _Pragma("unroll") for (int _i = 0; _i < 2; ++_i) \
;         __builtin_amdgcn_global_load_lds((const unsigned*)((const char*)(gbase) + voff[_i]), (LAS unsigned*)(lds + (bufoff) + ldsw + _i * 8192), 16, 0, 0); } while (0)
; #define G_LDA(dst, b, h) do { _Pragma("unroll") for (int m = 0; m < 4; ++m) _Pragma("unroll") for (int k = 0; k < 2; ++k) dst[m][k] = *(const LAS bf16x8*)(lds + G_SA(b, h) + aoff + m * 2048 + k * 1024); } while (0)
; #define G_LDB(dst, b, h) do { _Pragma("unroll") for (int n = 0; n < 2; ++n) _Pragma("unroll") for (int k = 0; k < 2; ++k) dst[n][k] = *(const LAS bf16x8*)(lds + G_SB(b, h) + boff + n * 2048 + k * 1024); } while (0)
; #define G_MMA(ai, bj, At, Bt) do { __builtin_amdgcn_s_setprio(1); _Pragma("unroll") for (int m = 0; m < 4; ++m) _Pragma("unroll") for (int n = 0; n < 2; ++n) _Pragma("unroll") for (int k = 0; k < 2; ++k) \
;         acc[ai][bj][m][n] = MFMA16(Bt[n][k], At[m][k], acc[ai][bj][m][n]); __builtin_amdgcn_s_setprio(0); } while (0)
; #define G_WAIT_V(n) asm volatile("s_waitcnt vmcnt(" #n ")" ::: "memory")
; #define G_WAIT_L(n) asm volatile("s_waitcnt lgkmcnt(" #n ")" ::: "memory")
; #define G_BAR __builtin_amdgcn_s_barrier()
; #define G_SCHED __builtin_amdgcn_sched_barrier(0)
; template <class Epi>
; __device__ __forceinline__ void gemm_phase(LAS unsigned char* lds, const bf16_t* Ag, const bf16_t* Btg, const int K, const int nM, const int nN, const Epi& E) {
;     ...
;             G_WAIT_V(6); G_BAR; G_MMA(1, 1, At, B1); G_BAR;
;             G_LDB(B0, 1, 0); G_SCHED; G_LDA(At, 1, 0); G_STAGE(G_SA(0, 1), a2 + hstep);
;             G_WAIT_L(8); G_BAR; G_WAIT_L(0); G_MMA(0, 0, At, B0); G_BAR; G_SCHED;
;             G_LDB(B1, 1, 1); G_STAGE(G_SB(1, 0), b3);
	s_setprio 1
	v_mfma_f32_16x16x32_bf16 v[68:71], v[236:239], v[156:159], v[68:71]
	v_mfma_f32_16x16x32_bf16 v[64:67], v[244:247], v[156:159], v[64:67]
	v_mfma_f32_16x16x32_bf16 v[52:55], v[236:239], v[164:167], v[52:55]
	v_mfma_f32_16x16x32_bf16 v[48:51], v[244:247], v[164:167], v[48:51]
	v_mfma_f32_16x16x32_bf16 v[36:39], v[236:239], v[184:187], v[36:39]
	v_mfma_f32_16x16x32_bf16 v[32:35], v[244:247], v[184:187], v[32:35]
	v_mfma_f32_16x16x32_bf16 v[20:23], v[236:239], v[228:231], v[20:23]
	v_mfma_f32_16x16x32_bf16 v[16:19], v[244:247], v[228:231], v[16:19]
	v_mfma_f32_16x16x32_bf16 v[68:71], v[240:243], v[160:163], v[68:71]
	v_mfma_f32_16x16x32_bf16 v[64:67], v[248:251], v[160:163], v[64:67]
	v_mfma_f32_16x16x32_bf16 v[52:55], v[240:243], v[180:183], v[52:55]
	v_mfma_f32_16x16x32_bf16 v[48:51], v[248:251], v[180:183], v[48:51]
	v_mfma_f32_16x16x32_bf16 v[36:39], v[240:243], v[224:227], v[36:39]
	v_mfma_f32_16x16x32_bf16 v[32:35], v[248:251], v[224:227], v[32:35]
	v_mfma_f32_16x16x32_bf16 v[20:23], v[240:243], v[232:235], v[20:23]
	v_mfma_f32_16x16x32_bf16 v[16:19], v[248:251], v[232:235], v[16:19]
	s_setprio 0
	s_add_i32 s26, 0, 0x18000
	v_add_u32_e32 v129, s26, v179
	s_barrier
	ds_read_b128 v[130:133], v129
	ds_read_b128 v[134:137], v129 offset:1024
	ds_read_b128 v[144:147], v129 offset:2048
	ds_read_b128 v[148:151], v129 offset:3072
	s_add_u32 s54, s54, 0x40000
	s_addc_u32 s55, s55, 0
	s_mov_b32 m0, s62
	ds_read_b128 v[156:159], v222 offset:32768
	ds_read_b128 v[160:163], v222 offset:33792
	ds_read_b128 v[164:167], v222 offset:34816
	ds_read_b128 v[180:183], v222 offset:35840
	ds_read_b128 v[184:187], v222 offset:36864
	ds_read_b128 v[224:227], v222 offset:37888
	ds_read_b128 v[228:231], v222 offset:38912
	global_load_lds_dwordx4 v0, s[54:55]
	s_mov_b32 m0, s63
	ds_read_b128 v[232:235], v222 offset:39936
	global_load_lds_dwordx4 v2, s[54:55]
	s_waitcnt lgkmcnt(8)
	s_barrier
	s_waitcnt lgkmcnt(0)
	s_setprio 1
	s_waitcnt lgkmcnt(0)
	v_mfma_f32_16x16x32_bf16 v[152:155], v[130:133], v[156:159], v[152:155]
	v_mfma_f32_16x16x32_bf16 v[138:141], v[144:147], v[156:159], v[138:141]
	v_mfma_f32_16x16x32_bf16 v[116:119], v[130:133], v[164:167], v[116:119]
	v_mfma_f32_16x16x32_bf16 v[112:115], v[144:147], v[164:167], v[112:115]
	v_mfma_f32_16x16x32_bf16 v[100:103], v[130:133], v[184:187], v[100:103]
	v_mfma_f32_16x16x32_bf16 v[96:99], v[144:147], v[184:187], v[96:99]
	v_mfma_f32_16x16x32_bf16 v[84:87], v[130:133], v[228:231], v[84:87]
	v_mfma_f32_16x16x32_bf16 v[80:83], v[144:147], v[228:231], v[80:83]
	v_mfma_f32_16x16x32_bf16 v[152:155], v[134:137], v[160:163], v[152:155]
	v_mfma_f32_16x16x32_bf16 v[140:143], v[148:151], v[160:163], v[138:141]
	v_mfma_f32_16x16x32_bf16 v[116:119], v[134:137], v[180:183], v[116:119]
	v_mfma_f32_16x16x32_bf16 v[112:115], v[148:151], v[180:183], v[112:115]
	v_mfma_f32_16x16x32_bf16 v[100:103], v[134:137], v[224:227], v[100:103]
	v_mfma_f32_16x16x32_bf16 v[96:99], v[148:151], v[224:227], v[96:99]
	v_mfma_f32_16x16x32_bf16 v[84:87], v[134:137], v[232:235], v[84:87]
	v_mfma_f32_16x16x32_bf16 v[80:83], v[148:151], v[232:235], v[80:83]
	s_setprio 0
	s_barrier
	s_add_i32 s54, 0, 0x1c000
	s_add_i32 s26, s26, s59
	v_add_u32_e32 v129, s54, v179
	s_mov_b32 m0, s26
	ds_read_b128 v[236:239], v129
	ds_read_b128 v[240:243], v129 offset:1024
	ds_read_b128 v[244:247], v129 offset:2048
	ds_read_b128 v[248:251], v129 offset:3072
	s_add_u32 s98, s52, 0x80
	s_addc_u32 s99, s53, 0
	global_load_lds_dwordx4 v0, s[98:99]
	s_add_i32 m0, s26, 0x2000
	s_nop 0
	global_load_lds_dwordx4 v2, s[98:99]
	s_barrier
; #define G_STAGE(bufoff, gbase) do { _Pragma("unroll") for (int _i = 0; _i < 2; ++_i) \
;         __builtin_amdgcn_global_load_lds((const unsigned*)((const char*)(gbase) + voff[_i]), (LAS unsigned*)(lds + (bufoff) + ldsw + _i * 8192), 16, 0, 0); } while (0)
; #define G_LDA(dst, b, h) do { _Pragma("unroll") for (int m = 0; m < 4; ++m) _Pragma("unroll") for (int k = 0; k < 2; ++k) dst[m][k] = *(const LAS bf16x8*)(lds + G_SA(b, h) + aoff + m * 2048 + k * 1024); } while (0)
; #define G_MMA(ai, bj, At, Bt) do { __builtin_amdgcn_s_setprio(1); _Pragma("unroll") for (int m = 0; m < 4; ++m) _Pragma("unroll") for (int n = 0; n < 2; ++n) _Pragma("unroll") for (int k = 0; k < 2; ++k) \
;         acc[ai][bj][m][n] = MFMA16(Bt[n][k], At[m][k], acc[ai][bj][m][n]); __builtin_amdgcn_s_setprio(0); } while (0)
; #define G_WAIT_V(n) asm volatile("s_waitcnt vmcnt(" #n ")" ::: "memory")
; #define G_WAIT_L(n) asm volatile("s_waitcnt lgkmcnt(" #n ")" ::: "memory")
; #define G_BAR __builtin_amdgcn_s_barrier()
; #define G_SCHED __builtin_amdgcn_sched_barrier(0)
; template <class Epi>
; __device__ __forceinline__ void gemm_phase(LAS unsigned char* lds, const bf16_t* Ag, const bf16_t* Btg, const int K, const int nM, const int nN, const Epi& E) {
;     ...
;         for (int t = 0; t < nt; t += 2) {
;     ...
;             G_BAR; G_WAIT_L(0); G_MMA(0, 1, At, B1); G_BAR;
;             G_LDA(At, 1, 1); G_STAGE(G_SA(1, 0), a3);
;             G_BAR; G_WAIT_L(0); G_MMA(1, 0, At, B0); G_BAR; G_SCHED;
;             G_STAGE(G_SB(1, 1), b3 + hstep);
;             G_WAIT_V(6); G_BAR; G_MMA(1, 1, At, B1); G_BAR;
	s_waitcnt lgkmcnt(0)
	s_setprio 1
	s_waitcnt lgkmcnt(0)
	v_mfma_f32_16x16x32_bf16 v[124:127], v[236:239], v[156:159], v[124:127]
	v_mfma_f32_16x16x32_bf16 v[120:123], v[244:247], v[156:159], v[120:123]
	v_mfma_f32_16x16x32_bf16 v[108:111], v[236:239], v[164:167], v[108:111]
	v_mfma_f32_16x16x32_bf16 v[104:107], v[244:247], v[164:167], v[104:107]
	v_mfma_f32_16x16x32_bf16 v[92:95], v[236:239], v[184:187], v[92:95]
	v_mfma_f32_16x16x32_bf16 v[88:91], v[244:247], v[184:187], v[88:91]
	v_mfma_f32_16x16x32_bf16 v[76:79], v[236:239], v[228:231], v[76:79]
	v_mfma_f32_16x16x32_bf16 v[72:75], v[244:247], v[228:231], v[72:75]
	v_mfma_f32_16x16x32_bf16 v[124:127], v[240:243], v[160:163], v[124:127]
	v_mfma_f32_16x16x32_bf16 v[120:123], v[248:251], v[160:163], v[120:123]
	v_mfma_f32_16x16x32_bf16 v[108:111], v[240:243], v[180:183], v[108:111]
	v_mfma_f32_16x16x32_bf16 v[104:107], v[248:251], v[180:183], v[104:107]
	v_mfma_f32_16x16x32_bf16 v[92:95], v[240:243], v[224:227], v[92:95]
	v_mfma_f32_16x16x32_bf16 v[88:91], v[248:251], v[224:227], v[88:91]
	v_mfma_f32_16x16x32_bf16 v[76:79], v[240:243], v[232:235], v[76:79]
	v_mfma_f32_16x16x32_bf16 v[72:75], v[248:251], v[232:235], v[72:75]
	s_setprio 0
	s_mov_b32 m0, s64
	s_barrier
	ds_read_b128 v[156:159], v222 offset:49152
	ds_read_b128 v[160:163], v222 offset:50176
	ds_read_b128 v[164:167], v222 offset:51200
	ds_read_b128 v[180:183], v222 offset:52224
	ds_read_b128 v[184:187], v222 offset:53248
	ds_read_b128 v[224:227], v222 offset:54272
	ds_read_b128 v[228:231], v222 offset:55296
	global_load_lds_dwordx4 v0, s[76:77]
	s_mov_b32 m0, s65
	ds_read_b128 v[232:235], v222 offset:56320
	global_load_lds_dwordx4 v2, s[76:77]
	s_barrier
	s_waitcnt lgkmcnt(0)
	s_setprio 1
	s_waitcnt lgkmcnt(0)
	v_mfma_f32_16x16x32_bf16 v[60:63], v[130:133], v[156:159], v[60:63]
	v_mfma_f32_16x16x32_bf16 v[56:59], v[144:147], v[156:159], v[56:59]
	v_mfma_f32_16x16x32_bf16 v[44:47], v[130:133], v[164:167], v[44:47]
	v_mfma_f32_16x16x32_bf16 v[40:43], v[144:147], v[164:167], v[40:43]
	v_mfma_f32_16x16x32_bf16 v[28:31], v[130:133], v[184:187], v[28:31]
	v_mfma_f32_16x16x32_bf16 v[24:27], v[144:147], v[184:187], v[24:27]
	v_mfma_f32_16x16x32_bf16 v[12:15], v[130:133], v[228:231], v[12:15]
	v_mfma_f32_16x16x32_bf16 v[8:11], v[144:147], v[228:231], v[8:11]
	v_mfma_f32_16x16x32_bf16 v[60:63], v[134:137], v[160:163], v[60:63]
	v_mfma_f32_16x16x32_bf16 v[56:59], v[148:151], v[160:163], v[56:59]
	v_mfma_f32_16x16x32_bf16 v[44:47], v[134:137], v[180:183], v[44:47]
	v_mfma_f32_16x16x32_bf16 v[40:43], v[148:151], v[180:183], v[40:43]
	v_mfma_f32_16x16x32_bf16 v[28:31], v[134:137], v[224:227], v[28:31]
	v_mfma_f32_16x16x32_bf16 v[24:27], v[148:151], v[224:227], v[24:27]
	v_mfma_f32_16x16x32_bf16 v[12:15], v[134:137], v[232:235], v[12:15]
	v_mfma_f32_16x16x32_bf16 v[8:11], v[148:151], v[232:235], v[8:11]
	s_setprio 0
	s_barrier
	s_add_u32 s52, s52, 0x40080
	s_addc_u32 s53, s53, 0
	s_add_i32 s26, s54, s59
	s_mov_b32 m0, s26
	s_nop 0
	global_load_lds_dwordx4 v0, s[52:53]
	s_add_i32 m0, s26, 0x2000
	s_nop 0
	global_load_lds_dwordx4 v2, s[52:53]
	s_waitcnt vmcnt(6)
	s_barrier
	s_setprio 1
	v_mfma_f32_16x16x32_bf16 v[68:71], v[236:239], v[156:159], v[68:71]
	v_mfma_f32_16x16x32_bf16 v[64:67], v[244:247], v[156:159], v[64:67]
	v_mfma_f32_16x16x32_bf16 v[52:55], v[236:239], v[164:167], v[52:55]
	v_mfma_f32_16x16x32_bf16 v[48:51], v[244:247], v[164:167], v[48:51]
	v_mfma_f32_16x16x32_bf16 v[36:39], v[236:239], v[184:187], v[36:39]
	v_mfma_f32_16x16x32_bf16 v[32:35], v[244:247], v[184:187], v[32:35]
	v_mfma_f32_16x16x32_bf16 v[20:23], v[236:239], v[228:231], v[20:23]
	v_mfma_f32_16x16x32_bf16 v[16:19], v[244:247], v[228:231], v[16:19]
	v_mfma_f32_16x16x32_bf16 v[68:71], v[240:243], v[160:163], v[68:71]
	v_mfma_f32_16x16x32_bf16 v[64:67], v[248:251], v[160:163], v[64:67]
	v_mfma_f32_16x16x32_bf16 v[52:55], v[240:243], v[180:183], v[52:55]
	v_mfma_f32_16x16x32_bf16 v[48:51], v[248:251], v[180:183], v[48:51]
	v_mfma_f32_16x16x32_bf16 v[36:39], v[240:243], v[224:227], v[36:39]
	v_mfma_f32_16x16x32_bf16 v[32:35], v[248:251], v[224:227], v[32:35]
	v_mfma_f32_16x16x32_bf16 v[20:23], v[240:243], v[232:235], v[20:23]
	v_mfma_f32_16x16x32_bf16 v[16:19], v[248:251], v[232:235], v[16:19]
	s_setprio 0
	s_add_i32 s72, s72, 2
	s_add_u32 s70, s70, 0x100
	s_addc_u32 s71, s71, 0
	s_add_u32 s50, s50, 0x100
	s_addc_u32 s51, s51, 0
	s_cmp_gt_u32 s72, 13
	s_barrier
	s_cbranch_scc1 .LBB0_852
